# out-proj tail: the 12 leftover tiles are split into 48 quarter units (one 128x128 quadrant per workgroup, other MFMA blocks skipped, hand-written quadrant epilogue); gate loads of the attention tails
# speedup vs baseline: 1.0824x; 1.0291x over previous
; DI unsigned pk2(float a, float b) { f32x2 v = {a, b}; bf16x2v r = __builtin_convertvector(v, bf16x2v); return __builtin_bit_cast(unsigned, r); }
; DI float bflo(unsigned w) { return __uint_as_float(w << 16); }
; DI float bfhi(unsigned w) { return __uint_as_float(w & 0xffff0000u); }
; DI void store_gated(const AttnState& st, const bf16_t* sg, bf16_t* mo, int hh) {
; #pragma unroll
;     for (int dt = 0; dt < 2; ++dt)
; #pragma unroll
;         for (int g = 0; g < 4; ++g) {
;             const int d = 32 * dt + 8 * g + 4 * hh;
;             const u32x2 gv = *(const u32x2*)(sg + d);
;             const f32x16& o = dt == 0 ? st.o0 : st.o1;
;             const float a0 = o[4 * g] * bflo(gv[0]), a1 = o[4 * g + 1] * bfhi(gv[0]), a2 = o[4 * g + 2] * bflo(gv[1]), a3 = o[4 * g + 3] * bfhi(gv[1]);
;             *(u32x2*)(mo + d) = (u32x2){pk2(a0, a1), pk2(a2, a3)};
;         }
; }
; template <int MODE>
; DI void prompt_unit(const Params& p, int b, int h, int qt, char* smem) {
;     ...
;     if (wave_valid && qpos < LP) store_gated(st, p.u + (rowb + qpos) * NU + gcol, p.mix + (rowb + qpos) * DM + (MODE == 0 ? 0 : 512) + h * 64, hh);
.LBB0_432:
	s_or_b64 exec, exec, s[8:9]
	v_cmp_gt_i32_e32 vcc, s88, v98
	s_and_saveexec_b64 s[0:1], vcc
	s_xor_b64 s[0:1], exec, s[0:1]
	s_cbranch_execz .LBB0_418
	v_lshlrev_b32_e32 v130, 1, v99
	v_lshl_add_u64 v[32:33], v[100:101], 0, v[130:131]
	global_load_dwordx2 v[40:41], v[32:33], off offset:3072
	global_load_dwordx2 v[42:43], v[32:33], off offset:3088
	global_load_dwordx2 v[44:45], v[32:33], off offset:3104
	global_load_dwordx2 v[46:47], v[32:33], off offset:3120
	global_load_dwordx2 v[48:49], v[32:33], off offset:3136
	global_load_dwordx2 v[50:51], v[32:33], off offset:3152
	global_load_dwordx2 v[52:53], v[32:33], off offset:3168
	global_load_dwordx2 v[54:55], v[32:33], off offset:3184
	v_lshlrev_b64 v[36:37], 11, v[96:97]
	s_lshl_b32 s10, s39, 1
	v_lshl_add_u64 v[36:37], s[70:71], 0, v[36:37]
	v_lshl_add_u64 v[36:37], v[36:37], 0, s[10:11]
	v_lshl_add_u64 v[36:37], v[36:37], 0, v[130:131]
	s_waitcnt vmcnt(7)
	v_lshlrev_b32_e32 v56, 16, v40
	v_and_b32_e32 v57, 0xffff0000, v40
	v_lshlrev_b32_e32 v58, 16, v41
	v_and_b32_e32 v59, 0xffff0000, v41
	v_pk_mul_f32 v[16:17], v[16:17], v[56:57]
	v_pk_mul_f32 v[18:19], v[18:19], v[58:59]
	v_cvt_pk_bf16_f32 v16, v16, v17
	v_cvt_pk_bf16_f32 v17, v18, v19
	global_store_dwordx2 v[36:37], v[16:17], off
	s_waitcnt vmcnt(7)
	v_lshlrev_b32_e32 v60, 16, v42
	v_and_b32_e32 v61, 0xffff0000, v42
	v_lshlrev_b32_e32 v62, 16, v43
	v_and_b32_e32 v63, 0xffff0000, v43
	v_pk_mul_f32 v[20:21], v[20:21], v[60:61]
	v_pk_mul_f32 v[22:23], v[22:23], v[62:63]
	v_cvt_pk_bf16_f32 v20, v20, v21
	v_cvt_pk_bf16_f32 v21, v22, v23
	global_store_dwordx2 v[36:37], v[20:21], off offset:16
	s_waitcnt vmcnt(7)
	v_lshlrev_b32_e32 v56, 16, v44
	v_and_b32_e32 v57, 0xffff0000, v44
	v_lshlrev_b32_e32 v58, 16, v45
	v_and_b32_e32 v59, 0xffff0000, v45
	v_pk_mul_f32 v[24:25], v[24:25], v[56:57]
	v_pk_mul_f32 v[26:27], v[26:27], v[58:59]
	v_cvt_pk_bf16_f32 v24, v24, v25
	v_cvt_pk_bf16_f32 v25, v26, v27
	global_store_dwordx2 v[36:37], v[24:25], off offset:32
	s_waitcnt vmcnt(7)
	v_lshlrev_b32_e32 v60, 16, v46
	v_and_b32_e32 v61, 0xffff0000, v46
	v_lshlrev_b32_e32 v62, 16, v47
	v_and_b32_e32 v63, 0xffff0000, v47
	v_pk_mul_f32 v[28:29], v[28:29], v[60:61]
	v_pk_mul_f32 v[30:31], v[30:31], v[62:63]
	v_cvt_pk_bf16_f32 v28, v28, v29
	v_cvt_pk_bf16_f32 v29, v30, v31
	global_store_dwordx2 v[36:37], v[28:29], off offset:48
	s_waitcnt vmcnt(7)
	v_lshlrev_b32_e32 v56, 16, v48
	v_and_b32_e32 v57, 0xffff0000, v48
	v_lshlrev_b32_e32 v58, 16, v49
	v_and_b32_e32 v59, 0xffff0000, v49
	v_pk_mul_f32 v[0:1], v[0:1], v[56:57]
	v_pk_mul_f32 v[2:3], v[2:3], v[58:59]
	v_cvt_pk_bf16_f32 v0, v0, v1
	v_cvt_pk_bf16_f32 v1, v2, v3
	global_store_dwordx2 v[36:37], v[0:1], off offset:64
	s_waitcnt vmcnt(7)
	v_lshlrev_b32_e32 v60, 16, v50
	v_and_b32_e32 v61, 0xffff0000, v50
	v_lshlrev_b32_e32 v62, 16, v51
	v_and_b32_e32 v63, 0xffff0000, v51
	v_pk_mul_f32 v[4:5], v[4:5], v[60:61]
	v_pk_mul_f32 v[6:7], v[6:7], v[62:63]
	v_cvt_pk_bf16_f32 v4, v4, v5
	v_cvt_pk_bf16_f32 v5, v6, v7
	global_store_dwordx2 v[36:37], v[4:5], off offset:80
	s_waitcnt vmcnt(7)
	v_lshlrev_b32_e32 v56, 16, v52
	v_and_b32_e32 v57, 0xffff0000, v52
	v_lshlrev_b32_e32 v58, 16, v53
	v_and_b32_e32 v59, 0xffff0000, v53
	v_pk_mul_f32 v[8:9], v[8:9], v[56:57]
	v_pk_mul_f32 v[10:11], v[10:11], v[58:59]
	v_cvt_pk_bf16_f32 v8, v8, v9
	v_cvt_pk_bf16_f32 v9, v10, v11
	global_store_dwordx2 v[36:37], v[8:9], off offset:96
	s_waitcnt vmcnt(7)
	v_lshlrev_b32_e32 v60, 16, v54
	v_and_b32_e32 v61, 0xffff0000, v54
	v_lshlrev_b32_e32 v62, 16, v55
	v_and_b32_e32 v63, 0xffff0000, v55
	v_pk_mul_f32 v[12:13], v[12:13], v[60:61]
	v_pk_mul_f32 v[14:15], v[14:15], v[62:63]
	v_cvt_pk_bf16_f32 v12, v12, v13
	v_cvt_pk_bf16_f32 v13, v14, v15
	global_store_dwordx2 v[36:37], v[12:13], off offset:112
	s_branch .LBB0_418

; DI unsigned pk2(float a, float b) { f32x2 v = {a, b}; bf16x2v r = __builtin_convertvector(v, bf16x2v); return __builtin_bit_cast(unsigned, r); }
; DI float bflo(unsigned w) { return __uint_as_float(w << 16); }
; DI float bfhi(unsigned w) { return __uint_as_float(w & 0xffff0000u); }
; DI void store_gated(const AttnState& st, const bf16_t* sg, bf16_t* mo, int hh) {
; #pragma unroll
;     for (int dt = 0; dt < 2; ++dt)
; #pragma unroll
;         for (int g = 0; g < 4; ++g) {
;             const int d = 32 * dt + 8 * g + 4 * hh;
;             const u32x2 gv = *(const u32x2*)(sg + d);
;             const f32x16& o = dt == 0 ? st.o0 : st.o1;
;             const float a0 = o[4 * g] * bflo(gv[0]), a1 = o[4 * g + 1] * bfhi(gv[0]), a2 = o[4 * g + 2] * bflo(gv[1]), a3 = o[4 * g + 3] * bfhi(gv[1]);
;             *(u32x2*)(mo + d) = (u32x2){pk2(a0, a1), pk2(a2, a3)};
;         }
; }
; template <int MODE>
; DI void prompt_unit(const Params& p, int b, int h, int qt, char* smem) {
;     ...
;     if (MODE == 1) { const float lt = st.l + __shfl_xor(st.l, 32); const float inv = 1.0f / lt; st.o0 = st.o0 * inv; st.o1 = st.o1 * inv; }
;     if (wave_valid && qpos < LP) store_gated(st, p.u + (rowb + qpos) * NU + gcol, p.mix + (rowb + qpos) * DM + (MODE == 0 ? 0 : 512) + h * 64, hh);
.LBB0_548:
	v_and_b32_e32 v33, 64, v174
	v_xor_b32_e32 v32, 32, v174
	v_add_u32_e32 v33, 64, v33
	v_cmp_lt_i32_e32 vcc, v32, v33
	s_nop 1
	v_cndmask_b32_e32 v32, v174, v32, vcc
	v_lshlrev_b32_e32 v32, 2, v32
	ds_bpermute_b32 v32, v32, v107
	v_cmp_gt_i32_e32 vcc, s88, v88
	s_and_b64 s[0:1], s[4:5], vcc
	s_and_saveexec_b64 s[4:5], s[0:1]
	s_xor_b64 s[0:1], exec, s[4:5]
	s_cbranch_execz .LBB0_507
	v_ashrrev_i32_e32 v89, 31, v88
	v_lshl_add_u64 v[34:35], v[88:89], 0, s[8:9]
	v_lshlrev_b64 v[36:37], 13, v[34:35]
	v_lshl_add_u64 v[36:37], s[68:69], 0, v[36:37]
	s_mov_b32 s7, s11
	v_lshl_add_u64 v[36:37], v[36:37], 0, s[6:7]
	v_lshl_add_u64 v[36:37], v[36:37], 0, s[28:29]
	v_lshlrev_b32_e32 v130, 1, v91
	v_lshl_add_u64 v[36:37], v[36:37], 0, v[130:131]
	global_load_dwordx2 v[48:49], v[36:37], off offset:0
	global_load_dwordx2 v[50:51], v[36:37], off offset:16
	global_load_dwordx2 v[52:53], v[36:37], off offset:32
	global_load_dwordx2 v[54:55], v[36:37], off offset:48
	global_load_dwordx2 v[56:57], v[36:37], off offset:64
	global_load_dwordx2 v[58:59], v[36:37], off offset:80
	global_load_dwordx2 v[60:61], v[36:37], off offset:96
	global_load_dwordx2 v[62:63], v[36:37], off offset:112
	s_waitcnt lgkmcnt(0)
	v_add_f32_e32 v40, v107, v32
	v_div_scale_f32 v41, s[4:5], v40, v40, 1.0
	v_rcp_f32_e32 v43, v41
	v_div_scale_f32 v42, vcc, 1.0, v40, 1.0
	v_fma_f32 v44, -v41, v43, 1.0
	v_fmac_f32_e32 v43, v44, v43
	v_mul_f32_e32 v44, v42, v43
	v_fma_f32 v45, -v41, v44, v42
	v_fmac_f32_e32 v44, v45, v43
	v_fma_f32 v41, -v41, v44, v42
	v_div_fmas_f32 v41, v41, v43, v44
	v_div_fixup_f32 v40, v41, v40, 1.0
	v_lshlrev_b64 v[34:35], 11, v[34:35]
	v_lshl_add_u64 v[34:35], s[70:71], 0, v[34:35]
	v_lshl_add_u64 v[34:35], v[34:35], 0, s[6:7]
	v_lshl_add_u64 v[34:35], v[34:35], 0, v[130:131]
	s_waitcnt vmcnt(7)
	v_lshlrev_b32_e32 v64, 16, v48
	v_and_b32_e32 v65, 0xffff0000, v48
	v_lshlrev_b32_e32 v66, 16, v49
	v_and_b32_e32 v67, 0xffff0000, v49
	v_pk_mul_f32 v[16:17], v[16:17], v[40:41] op_sel_hi:[1,0]
	v_pk_mul_f32 v[18:19], v[18:19], v[40:41] op_sel_hi:[1,0]
	v_pk_mul_f32 v[16:17], v[16:17], v[64:65]
	v_pk_mul_f32 v[18:19], v[18:19], v[66:67]
	v_cvt_pk_bf16_f32 v16, v16, v17
	v_cvt_pk_bf16_f32 v17, v18, v19
	global_store_dwordx2 v[34:35], v[16:17], off offset:1024
	s_waitcnt vmcnt(7)
	v_lshlrev_b32_e32 v68, 16, v50
	v_and_b32_e32 v69, 0xffff0000, v50
	v_lshlrev_b32_e32 v70, 16, v51
	v_and_b32_e32 v71, 0xffff0000, v51
	v_pk_mul_f32 v[20:21], v[20:21], v[40:41] op_sel_hi:[1,0]
	v_pk_mul_f32 v[22:23], v[22:23], v[40:41] op_sel_hi:[1,0]
	v_pk_mul_f32 v[20:21], v[20:21], v[68:69]
	v_pk_mul_f32 v[22:23], v[22:23], v[70:71]
	v_cvt_pk_bf16_f32 v20, v20, v21
	v_cvt_pk_bf16_f32 v21, v22, v23
	global_store_dwordx2 v[34:35], v[20:21], off offset:1040
	s_waitcnt vmcnt(7)
	v_lshlrev_b32_e32 v64, 16, v52
	v_and_b32_e32 v65, 0xffff0000, v52
	v_lshlrev_b32_e32 v66, 16, v53
	v_and_b32_e32 v67, 0xffff0000, v53
	v_pk_mul_f32 v[24:25], v[24:25], v[40:41] op_sel_hi:[1,0]
	v_pk_mul_f32 v[26:27], v[26:27], v[40:41] op_sel_hi:[1,0]
	v_pk_mul_f32 v[24:25], v[24:25], v[64:65]
	v_pk_mul_f32 v[26:27], v[26:27], v[66:67]
	v_cvt_pk_bf16_f32 v24, v24, v25
	v_cvt_pk_bf16_f32 v25, v26, v27
	global_store_dwordx2 v[34:35], v[24:25], off offset:1056
	s_waitcnt vmcnt(7)
	v_lshlrev_b32_e32 v68, 16, v54
	v_and_b32_e32 v69, 0xffff0000, v54
	v_lshlrev_b32_e32 v70, 16, v55
	v_and_b32_e32 v71, 0xffff0000, v55
	v_pk_mul_f32 v[28:29], v[28:29], v[40:41] op_sel_hi:[1,0]
	v_pk_mul_f32 v[30:31], v[30:31], v[40:41] op_sel_hi:[1,0]
	v_pk_mul_f32 v[28:29], v[28:29], v[68:69]
	v_pk_mul_f32 v[30:31], v[30:31], v[70:71]
	v_cvt_pk_bf16_f32 v28, v28, v29
	v_cvt_pk_bf16_f32 v29, v30, v31
	global_store_dwordx2 v[34:35], v[28:29], off offset:1072
	s_waitcnt vmcnt(7)
	v_lshlrev_b32_e32 v64, 16, v56
	v_and_b32_e32 v65, 0xffff0000, v56
	v_lshlrev_b32_e32 v66, 16, v57
	v_and_b32_e32 v67, 0xffff0000, v57
	v_pk_mul_f32 v[0:1], v[0:1], v[40:41] op_sel_hi:[1,0]
	v_pk_mul_f32 v[2:3], v[2:3], v[40:41] op_sel_hi:[1,0]
	v_pk_mul_f32 v[0:1], v[0:1], v[64:65]
	v_pk_mul_f32 v[2:3], v[2:3], v[66:67]
	v_cvt_pk_bf16_f32 v0, v0, v1
	v_cvt_pk_bf16_f32 v1, v2, v3
	global_store_dwordx2 v[34:35], v[0:1], off offset:1088
	s_waitcnt vmcnt(7)
	v_lshlrev_b32_e32 v68, 16, v58
	v_and_b32_e32 v69, 0xffff0000, v58
	v_lshlrev_b32_e32 v70, 16, v59
	v_and_b32_e32 v71, 0xffff0000, v59
	v_pk_mul_f32 v[4:5], v[4:5], v[40:41] op_sel_hi:[1,0]
	v_pk_mul_f32 v[6:7], v[6:7], v[40:41] op_sel_hi:[1,0]
	v_pk_mul_f32 v[4:5], v[4:5], v[68:69]
	v_pk_mul_f32 v[6:7], v[6:7], v[70:71]
	v_cvt_pk_bf16_f32 v4, v4, v5
	v_cvt_pk_bf16_f32 v5, v6, v7
	global_store_dwordx2 v[34:35], v[4:5], off offset:1104
	s_waitcnt vmcnt(7)
	v_lshlrev_b32_e32 v64, 16, v60
	v_and_b32_e32 v65, 0xffff0000, v60
	v_lshlrev_b32_e32 v66, 16, v61
	v_and_b32_e32 v67, 0xffff0000, v61
	v_pk_mul_f32 v[8:9], v[8:9], v[40:41] op_sel_hi:[1,0]
	v_pk_mul_f32 v[10:11], v[10:11], v[40:41] op_sel_hi:[1,0]
	v_pk_mul_f32 v[8:9], v[8:9], v[64:65]
	v_pk_mul_f32 v[10:11], v[10:11], v[66:67]
	v_cvt_pk_bf16_f32 v8, v8, v9
	v_cvt_pk_bf16_f32 v9, v10, v11
	global_store_dwordx2 v[34:35], v[8:9], off offset:1120
	s_waitcnt vmcnt(7)
	v_lshlrev_b32_e32 v68, 16, v62
	v_and_b32_e32 v69, 0xffff0000, v62
	v_lshlrev_b32_e32 v70, 16, v63
	v_and_b32_e32 v71, 0xffff0000, v63
	v_pk_mul_f32 v[12:13], v[12:13], v[40:41] op_sel_hi:[1,0]
	v_pk_mul_f32 v[14:15], v[14:15], v[40:41] op_sel_hi:[1,0]
	v_pk_mul_f32 v[12:13], v[12:13], v[68:69]
	v_pk_mul_f32 v[14:15], v[14:15], v[70:71]
	v_cvt_pk_bf16_f32 v12, v12, v13
	v_cvt_pk_bf16_f32 v13, v14, v15
	global_store_dwordx2 v[34:35], v[12:13], off offset:1136
	s_branch .LBB0_507

; #define PG8_STAGE(bufoff, gbase, voff) do { _Pragma("unroll") for (int _i = 0; _i < 2; ++_i) \
;         __builtin_amdgcn_global_load_lds((const unsigned*)((const char*)(gbase) + (voff)[_i]), (PG8_LAS unsigned*)(lds + (bufoff) + ldsw + _i * 8192), 16, 0, 0); } while (0)
; #define PG8_WAIT_V(n) asm volatile("s_waitcnt vmcnt(" #n ")" ::: "memory")
; #define PG8_BAR __builtin_amdgcn_s_barrier()
; template <class Epi, class Sched, bool ALIGN_EPI = false, bool SP2 = false>
; __device__ __forceinline__ void gemm_phase(PG8_LAS unsigned char* lds, const Gemm g, const Sched& S, const Epi& E) {
;     ...
;     const char* cA = (const char*)g.A + (size_t)cur.pm * tstep; const char* cB = (const char*)g.Bt + (size_t)cur.pn * tstep;
;     S.a_ready(cur);
;     if constexpr (SP2) {
;         PG8_STAGE(PG8_SB(0, 0), cB, voffB); PG8_STAGE(PG8_SB(0, 1), cB + hstep, voffB); PG8_STAGE(PG8_SA(0, 0), cA, voffA); PG8_STAGE(PG8_SA(0, 1), cA + hstep, voffA);
;         if (wr == 1) PG8_BAR;
;         PG8_WAIT_V(2); PG8_BAR;
;         PG8_STAGE(PG8_SB(1, 0), cB + kstep, voffB); PG8_STAGE(PG8_SA(1, 0), cA + kstep, voffA); PG8_STAGE(PG8_SB(1, 1), cB + hstep + kstep, voffB);
;         PG8_WAIT_V(6); PG8_BAR;
.LBB0_607:
	v_bfe_u32 v8, v138, 4, 2
	s_lshl_b32 s6, s6, 5
	v_lshlrev_b32_e32 v9, 4, v8
	v_lshlrev_b32_e32 v11, 2, v173
	s_and_b32 s12, s6, 0x60
	s_mov_b64 s[74:75], 0x80
	v_lshl_or_b32 v158, s7, 6, v173
	v_lshl_or_b32 v10, v173, 6, v9
	s_lshl_b32 s7, s7, 13
	v_and_b32_e32 v11, 32, v11
	v_or_b32_e32 v9, v9, v171
	s_lshl_b32 s6, s12, 7
	s_add_i32 m0, s0, 0x18000
	v_lshl_add_u64 v[6:7], v[6:7], 0, s[74:75]
	v_bitop3_b32 v10, v10, s7, v11 bitop3:0xde
	v_bitop3_b32 v9, s6, v9, v172 bitop3:0xf6
	s_waitcnt vmcnt(2)
	s_barrier
	global_load_lds_dwordx4 v[6:7], off
	v_lshl_add_u64 v[2:3], v[2:3], 0, s[74:75]
	s_add_i32 m0, s0, 0x1a000
	s_add_i32 s6, s0, 0x8000
	s_add_i32 s7, s0, 0xa000
	global_load_lds_dwordx4 v[2:3], off
	v_lshl_add_u64 v[0:1], v[0:1], 0, s[74:75]
	s_mov_b32 m0, s6
	s_add_u32 s10, s98, 0x40080
	global_load_lds_dwordx4 v[0:1], off
	v_lshl_add_u64 v[0:1], v[4:5], 0, s[74:75]
	s_mov_b32 m0, s7
	s_addc_u32 s11, s99, 0
	global_load_lds_dwordx4 v[0:1], off
	s_add_i32 m0, s0, 0x1c000
	v_lshl_add_u64 v[0:1], s[10:11], 0, v[142:143]
	global_load_lds_dwordx4 v[0:1], off
	v_lshl_add_u64 v[0:1], s[10:11], 0, v[146:147]
	s_add_i32 m0, s0, 0x1e000
	s_cmpk_lt_u32 s8, 0x100
	global_load_lds_dwordx4 v[0:1], off
	v_lshlrev_b32_e32 v0, 8, v138
	v_and_b32_e32 v0, 0x38000, v0
	v_lshlrev_b32_e32 v1, 11, v169
	v_or3_b32 v0, v139, v0, v1
	s_cselect_b64 s[80:81], -1, 0
	s_ashr_i32 s9, s33, 31
	s_ashr_i32 s10, s2, 31
	v_add_u32_e32 v134, v0, v168
	v_lshlrev_b32_e32 v0, 4, v170
	s_mov_b32 s17, 0x18000
	s_mov_b32 s18, 0x1c000
	s_waitcnt vmcnt(6)
	s_add_u32 s82, s54, 0x4000000
	v_lshl_or_b32 v159, v8, 3, s12
	v_and_b32_e32 v0, 0x78000, v0
	s_mov_b32 s11, 0x10000
	s_mov_b32 s12, 0x14000
	s_addc_u32 s83, s55, 0
	v_or3_b32 v0, v139, v0, v1
	s_addk_i32 s11, 0x100
	s_addk_i32 s12, 0x100
	s_mov_b32 s84, 0xffff0000
	s_addk_i32 s17, 0x100
	s_addk_i32 s18, 0x100
	s_mov_b32 s8, 0
	s_mov_b32 s100, 15
	v_cmp_eq_u32_e64 s[36:37], 0, v8
	v_mov_b32_e32 v135, v133
	v_add_u32_e32 v136, v0, v168
	v_mov_b32_e32 v137, v133
	v_mov_b64_e32 v[138:139], 0x10c
	v_mov_b64_e32 v[148:149], 0x10b
	v_add_u32_e32 v160, s11, v9
	v_add_u32_e32 v161, s12, v9
	v_add_u32_e32 v162, 0x100, v10
	s_movk_i32 s13, 0x40ff
	s_mov_b32 s14, 0x7e07e07f
	s_movk_i32 s15, 0xefc0
	s_movk_i32 s16, 0x1000
	s_mov_b32 s85, -1
	v_add_u32_e32 v163, s17, v9
	v_add_u32_e32 v164, s18, v9
	s_barrier
	s_branch .LBB0_610

;     __host__ __device__ bool next(int i, Unit& u) const {
;         const long L = (long)i * G + c; if (L >= nwg) return false;
;         int wgid = (int)L; { const int q = nwg / NXCD, r = nwg % NXCD, xcd = wgid % NXCD, off = wgid / NXCD; wgid = (xcd < r ? xcd * (q + 1) : r * (q + 1) + (xcd - r) * q) + off; }
;         const int nig = WGM * nN, gid = wgid / nig, fm = gid * WGM, gsz = (nM - fm) < WGM ? (nM - fm) : WGM;
;         u.pm = fm + ((wgid % nig) % gsz); u.pn = (wgid % nig) / gsz; return true;
;     }
; template <class Epi, class Sched, bool ALIGN_EPI = false, bool SP2 = false>
; __device__ __forceinline__ void gemm_phase(PG8_LAS unsigned char* lds, const Gemm g, const Sched& S, const Epi& E) {
;     ...
;     for (;;) {
;         const bool has_next = S.next(ui + 1, nxt);
;         const char* nA = has_next ? (const char*)g.A + (size_t)nxt.pm * tstep : cA; const char* nB = has_next ? (const char*)g.Bt + (size_t)nxt.pn * tstep : cB;
.LBB0_609:
	s_mov_b32 s100, s101
	s_andn2_b64 vcc, exec, s[38:39]
	s_mov_b32 s42, s86
	s_mov_b32 s94, s88
	s_mov_b64 s[98:99], s[92:93]
	s_mov_b64 s[96:97], s[90:91]
	s_cbranch_vccz .LBB0_703
.LBB0_610:
	s_add_i32 s8, s8, 1
	s_mul_i32 s19, s8, s9
	s_mul_hi_u32 s20, s8, s33
	s_add_i32 s20, s20, s19
	s_mul_i32 s19, s8, s33
	s_add_u32 s90, s19, s2
	s_addc_u32 s91, s20, s10
	s_mov_b32 s101, 15
	s_cmp_lg_u32 s8, 1
	s_cbranch_scc1 .Lp3q_hdr_done
	s_lshr_b32 s19, s2, 2
	s_add_i32 s90, s19, 0x100
	s_cmp_lt_u32 s2, 48
	s_cselect_b32 s90, s90, 0x7fffffff
	s_mov_b32 s91, 0
	s_and_b32 s19, s2, 3
	s_lshl_b32 s101, 1, s19
.Lp3q_hdr_done:
	v_cmp_gt_i64_e32 vcc, s[90:91], v[148:149]
	v_cmp_lt_i64_e64 s[38:39], s[90:91], v[138:139]
	s_cbranch_vccnz .LBB0_616
	s_ashr_i32 s19, s90, 31
	s_lshr_b32 s19, s19, 29
	s_add_i32 s19, s90, s19
	s_and_b32 s20, s19, -8
	s_sub_i32 s20, s90, s20
	s_cmp_gt_i32 s20, 3
	s_mov_b64 s[86:87], -1
	s_cbranch_scc0 .LBB0_613
	s_mul_i32 s21, s20, 33
	s_add_i32 s21, s21, 4
	s_mov_b64 s[86:87], 0

; #define PG8_STAGE(bufoff, gbase, voff) do { _Pragma("unroll") for (int _i = 0; _i < 2; ++_i) \
;         __builtin_amdgcn_global_load_lds((const unsigned*)((const char*)(gbase) + (voff)[_i]), (PG8_LAS unsigned*)(lds + (bufoff) + ldsw + _i * 8192), 16, 0, 0); } while (0)
; #define PG8_LDA(dst, b, h) do { _Pragma("unroll") for (int m = 0; m < 4; ++m) _Pragma("unroll") for (int k = 0; k < 2; ++k) dst[m][k] = *(const PG8_LAS bf16x8*)(lds + PG8_SA(b, h) + aoff + m * 2048 + k * 1024); } while (0)
; #define PG8_LDB(dst, b, h) do { _Pragma("unroll") for (int n = 0; n < 2; ++n) _Pragma("unroll") for (int k = 0; k < 2; ++k) dst[n][k] = *(const PG8_LAS bf16x8*)(lds + PG8_SB(b, h) + boff + n * 2048 + k * 1024); } while (0)
; #define PG8_MMA(ai, bj, At, Bt) do { __builtin_amdgcn_s_setprio(1); _Pragma("unroll") for (int m = 0; m < 4; ++m) _Pragma("unroll") for (int n = 0; n < 2; ++n) _Pragma("unroll") for (int k = 0; k < 2; ++k) \
;         acc[ai][bj][m][n] = __builtin_amdgcn_mfma_f32_16x16x32_bf16(Bt[n][k], At[m][k], acc[ai][bj][m][n], 0, 0, 0); __builtin_amdgcn_s_setprio(0); } while (0)
; #define PG8_WAIT_V(n) asm volatile("s_waitcnt vmcnt(" #n ")" ::: "memory")
; #define PG8_BAR __builtin_amdgcn_s_barrier()
; template <class Epi, class Sched, bool ALIGN_EPI = false, bool SP2 = false>
; __device__ __forceinline__ void gemm_phase(PG8_LAS unsigned char* lds, const Gemm g, const Sched& S, const Epi& E) {
;     ...
;         for (int t = 0; t < nt; t += 2) {
;             const bool last = (t == nt - 2);
;             const char* a1 = cA + (size_t)(t + 1) * kstep;
;             const char* a2 = last ? nA : cA + (size_t)(t + 2) * kstep; const char* b2 = last ? nB : cB + (size_t)(t + 2) * kstep;
;             const char* a3 = a2 + kstep; const char* b3 = b2 + kstep;
;             if (last && has_next) S.a_ready(nxt);
;             if constexpr (SP2) {
;             PG8_LDB(B0, 0, 0); PG8_LDB(B1, 0, 1); PG8_SCHED; PG8_LDA(At, 0, 0); PG8_STAGE(PG8_SA(1, 1), a1 + hstep, voffA);
;             PG8_WAIT_V(8); PG8_WAIT_L(0); PG8_BAR; PG8_MMA(0, 0, At, B0); PG8_MMA(0, 1, At, B1); PG8_BAR; PG8_SCHED;
;             PG8_LDA(At, 0, 1); PG8_STAGE(PG8_SB(0, 0), b2, voffB); PG8_STAGE(PG8_SB(0, 1), b2 + hstep, voffB); PG8_STAGE(PG8_SA(0, 0), a2, voffA);
;             PG8_WAIT_V(8); PG8_WAIT_L(0); PG8_BAR; PG8_MMA(1, 0, At, B0); PG8_MMA(1, 1, At, B1); PG8_BAR; PG8_SCHED;
.LBB0_617:
	ds_read_b128 v[150:153], v160
	ds_read_b128 v[154:157], v160 offset:1024
	ds_read_b128 v[168:171], v160 offset:2048
	ds_read_b128 v[176:179], v160 offset:3072
	ds_read_b128 v[180:183], v161
	ds_read_b128 v[184:187], v161 offset:1024
	ds_read_b128 v[188:191], v161 offset:2048
	ds_read_b128 v[192:195], v161 offset:3072
	s_add_u32 s22, s96, 0xfffc0080
	s_addc_u32 s23, s97, -1
	s_cmp_eq_u32 s21, 12
	s_cselect_b32 vcc_hi, s19, s23
	s_cselect_b32 vcc_lo, s43, s22
	s_cselect_b32 s99, s87, s20
	s_cselect_b32 s98, s89, s95
	v_lshl_add_u64 v[172:173], s[96:97], 0, v[134:135]
	s_add_i32 m0, s0, 0xc000
	ds_read_b128 v[196:199], v162
	ds_read_b128 v[200:203], v162 offset:1024
	ds_read_b128 v[204:207], v162 offset:2048
	ds_read_b128 v[208:211], v162 offset:3072
	ds_read_b128 v[212:215], v162 offset:4096
	ds_read_b128 v[216:219], v162 offset:5120
	ds_read_b128 v[220:223], v162 offset:6144
	ds_read_b128 v[224:227], v162 offset:7168
	global_load_lds_dwordx4 v[172:173], off
	v_lshl_add_u64 v[172:173], s[96:97], 0, v[136:137]
	s_add_i32 m0, s0, 0xe000
	s_nop 0
	global_load_lds_dwordx4 v[172:173], off
	s_waitcnt vmcnt(8)
	s_waitcnt lgkmcnt(0)
	s_barrier
	s_setprio 1
	s_waitcnt lgkmcnt(0)
	s_bitcmp1_b32 s100, 0
	s_cbranch_scc0 .Lp3q_skip_0
	v_mfma_f32_16x16x32_bf16 v[124:127], v[150:153], v[196:199], v[124:127]
	v_mfma_f32_16x16x32_bf16 v[120:123], v[168:171], v[196:199], v[120:123]
	v_mfma_f32_16x16x32_bf16 v[108:111], v[150:153], v[204:207], v[108:111]
	v_mfma_f32_16x16x32_bf16 v[104:107], v[168:171], v[204:207], v[104:107]
	v_mfma_f32_16x16x32_bf16 v[92:95], v[150:153], v[212:215], v[92:95]
	v_mfma_f32_16x16x32_bf16 v[88:91], v[168:171], v[212:215], v[88:91]
	v_mfma_f32_16x16x32_bf16 v[76:79], v[150:153], v[220:223], v[76:79]
	v_mfma_f32_16x16x32_bf16 v[72:75], v[168:171], v[220:223], v[72:75]
	v_mfma_f32_16x16x32_bf16 v[124:127], v[154:157], v[200:203], v[124:127]
	v_mfma_f32_16x16x32_bf16 v[120:123], v[176:179], v[200:203], v[120:123]
	v_mfma_f32_16x16x32_bf16 v[108:111], v[154:157], v[208:211], v[108:111]
	v_mfma_f32_16x16x32_bf16 v[104:107], v[176:179], v[208:211], v[104:107]
	v_mfma_f32_16x16x32_bf16 v[92:95], v[154:157], v[216:219], v[92:95]
	v_mfma_f32_16x16x32_bf16 v[88:91], v[176:179], v[216:219], v[88:91]
	v_mfma_f32_16x16x32_bf16 v[76:79], v[154:157], v[224:227], v[76:79]
	v_mfma_f32_16x16x32_bf16 v[72:75], v[176:179], v[224:227], v[72:75]
.Lp3q_skip_0:
	s_setprio 0
	s_setprio 1
	s_bitcmp1_b32 s100, 1
	s_cbranch_scc0 .Lp3q_skip_1
	v_mfma_f32_16x16x32_bf16 v[116:119], v[180:183], v[196:199], v[116:119]
	v_mfma_f32_16x16x32_bf16 v[112:115], v[188:191], v[196:199], v[112:115]
	v_mfma_f32_16x16x32_bf16 v[100:103], v[180:183], v[204:207], v[100:103]
	v_mfma_f32_16x16x32_bf16 v[96:99], v[188:191], v[204:207], v[96:99]
	v_mfma_f32_16x16x32_bf16 v[84:87], v[180:183], v[212:215], v[84:87]
	v_mfma_f32_16x16x32_bf16 v[80:83], v[188:191], v[212:215], v[80:83]
	v_mfma_f32_16x16x32_bf16 v[68:71], v[180:183], v[220:223], v[68:71]
	v_mfma_f32_16x16x32_bf16 v[64:67], v[188:191], v[220:223], v[64:67]
	v_mfma_f32_16x16x32_bf16 v[116:119], v[184:187], v[200:203], v[116:119]
	v_mfma_f32_16x16x32_bf16 v[112:115], v[192:195], v[200:203], v[112:115]
	v_mfma_f32_16x16x32_bf16 v[100:103], v[184:187], v[208:211], v[100:103]
	v_mfma_f32_16x16x32_bf16 v[96:99], v[192:195], v[208:211], v[96:99]
	v_mfma_f32_16x16x32_bf16 v[84:87], v[184:187], v[216:219], v[84:87]
	v_mfma_f32_16x16x32_bf16 v[80:83], v[192:195], v[216:219], v[80:83]
	v_mfma_f32_16x16x32_bf16 v[68:71], v[184:187], v[224:227], v[68:71]
	v_mfma_f32_16x16x32_bf16 v[64:67], v[192:195], v[224:227], v[64:67]
; #define PG8_STAGE(bufoff, gbase, voff) do { _Pragma("unroll") for (int _i = 0; _i < 2; ++_i) \
;         __builtin_amdgcn_global_load_lds((const unsigned*)((const char*)(gbase) + (voff)[_i]), (PG8_LAS unsigned*)(lds + (bufoff) + ldsw + _i * 8192), 16, 0, 0); } while (0)
; #define PG8_LDA(dst, b, h) do { _Pragma("unroll") for (int m = 0; m < 4; ++m) _Pragma("unroll") for (int k = 0; k < 2; ++k) dst[m][k] = *(const PG8_LAS bf16x8*)(lds + PG8_SA(b, h) + aoff + m * 2048 + k * 1024); } while (0)
; #define PG8_LDB(dst, b, h) do { _Pragma("unroll") for (int n = 0; n < 2; ++n) _Pragma("unroll") for (int k = 0; k < 2; ++k) dst[n][k] = *(const PG8_LAS bf16x8*)(lds + PG8_SB(b, h) + boff + n * 2048 + k * 1024); } while (0)
; #define PG8_MMA(ai, bj, At, Bt) do { __builtin_amdgcn_s_setprio(1); _Pragma("unroll") for (int m = 0; m < 4; ++m) _Pragma("unroll") for (int n = 0; n < 2; ++n) _Pragma("unroll") for (int k = 0; k < 2; ++k) \
;         acc[ai][bj][m][n] = __builtin_amdgcn_mfma_f32_16x16x32_bf16(Bt[n][k], At[m][k], acc[ai][bj][m][n], 0, 0, 0); __builtin_amdgcn_s_setprio(0); } while (0)
; #define PG8_BAR __builtin_amdgcn_s_barrier()
; template <class Epi, class Sched, bool ALIGN_EPI = false, bool SP2 = false>
; __device__ __forceinline__ void gemm_phase(PG8_LAS unsigned char* lds, const Gemm g, const Sched& S, const Epi& E) {
;     ...
;             if constexpr (SP2) {
;             PG8_LDB(B0, 0, 0); PG8_LDB(B1, 0, 1); PG8_SCHED; PG8_LDA(At, 0, 0); PG8_STAGE(PG8_SA(1, 1), a1 + hstep, voffA);
;             PG8_WAIT_V(8); PG8_WAIT_L(0); PG8_BAR; PG8_MMA(0, 0, At, B0); PG8_MMA(0, 1, At, B1); PG8_BAR; PG8_SCHED;
;             PG8_LDA(At, 0, 1); PG8_STAGE(PG8_SB(0, 0), b2, voffB); PG8_STAGE(PG8_SB(0, 1), b2 + hstep, voffB); PG8_STAGE(PG8_SA(0, 0), a2, voffA);
;             PG8_WAIT_V(8); PG8_WAIT_L(0); PG8_BAR; PG8_MMA(1, 0, At, B0); PG8_MMA(1, 1, At, B1); PG8_BAR; PG8_SCHED;
;             PG8_LDB(B0, 1, 0); PG8_LDB(B1, 1, 1); PG8_SCHED; PG8_LDA(At, 1, 0); PG8_STAGE(PG8_SA(0, 1), a2 + hstep, voffA);
;             PG8_WAIT_V(8); PG8_WAIT_L(0); PG8_BAR; PG8_MMA(0, 0, At, B0); PG8_MMA(0, 1, At, B1); PG8_BAR; PG8_SCHED;
;             PG8_LDA(At, 1, 1); PG8_STAGE(PG8_SB(1, 0), b3, voffB); PG8_STAGE(PG8_SB(1, 1), b3 + hstep, voffB); PG8_STAGE(PG8_SA(1, 0), a3, voffA);
;             PG8_WAIT_V(8); PG8_WAIT_L(0); PG8_BAR; PG8_MMA(1, 0, At, B0); PG8_MMA(1, 1, At, B1); PG8_BAR; PG8_SCHED;
.Lp3q_skip_1:
	s_setprio 0
	s_barrier
	s_add_i32 s22, s11, s3
	v_lshl_add_u64 v[172:173], s[98:99], 0, v[142:143]
	s_mov_b32 m0, s22
	ds_read_b128 v[196:199], v162 offset:16384
	ds_read_b128 v[200:203], v162 offset:17408
	ds_read_b128 v[204:207], v162 offset:18432
	ds_read_b128 v[208:211], v162 offset:19456
	ds_read_b128 v[212:215], v162 offset:20480
	ds_read_b128 v[216:219], v162 offset:21504
	ds_read_b128 v[220:223], v162 offset:22528
	ds_read_b128 v[224:227], v162 offset:23552
	global_load_lds_dwordx4 v[172:173], off
	s_add_i32 m0, s22, 0x2000
	s_add_u32 s22, s98, 0x40000
	v_lshl_add_u64 v[228:229], s[98:99], 0, v[146:147]
	s_addc_u32 s23, s99, 0
	s_add_i32 s24, s12, s3
	global_load_lds_dwordx4 v[228:229], off
	v_lshl_add_u64 v[230:231], s[22:23], 0, v[142:143]
	s_mov_b32 m0, s24
	v_lshl_add_u64 v[232:233], vcc, 0, v[144:145]
	global_load_lds_dwordx4 v[230:231], off
	v_lshl_add_u64 v[230:231], s[22:23], 0, v[146:147]
	s_add_i32 m0, s24, 0x2000
	s_nop 0
	global_load_lds_dwordx4 v[230:231], off
	v_lshl_add_u64 v[230:231], vcc, 0, v[140:141]
	s_mov_b32 m0, s0
	s_nop 0
	global_load_lds_dwordx4 v[230:231], off
	s_mov_b32 m0, s1
	s_nop 0
	global_load_lds_dwordx4 v[232:233], off
	s_waitcnt vmcnt(8)
	s_waitcnt lgkmcnt(0)
	s_barrier
	s_setprio 1
	s_waitcnt lgkmcnt(0)
	s_bitcmp1_b32 s100, 2
	s_cbranch_scc0 .Lp3q_skip_2
	v_mfma_f32_16x16x32_bf16 v[60:63], v[150:153], v[196:199], v[60:63]
	v_mfma_f32_16x16x32_bf16 v[56:59], v[168:171], v[196:199], v[56:59]
	v_mfma_f32_16x16x32_bf16 v[44:47], v[150:153], v[204:207], v[44:47]
	v_mfma_f32_16x16x32_bf16 v[40:43], v[168:171], v[204:207], v[40:43]
	v_mfma_f32_16x16x32_bf16 v[28:31], v[150:153], v[212:215], v[28:31]
	v_mfma_f32_16x16x32_bf16 v[24:27], v[168:171], v[212:215], v[24:27]
	v_mfma_f32_16x16x32_bf16 v[12:15], v[150:153], v[220:223], v[12:15]
	v_mfma_f32_16x16x32_bf16 v[8:11], v[168:171], v[220:223], v[8:11]
	v_mfma_f32_16x16x32_bf16 v[60:63], v[154:157], v[200:203], v[60:63]
	v_mfma_f32_16x16x32_bf16 v[56:59], v[176:179], v[200:203], v[56:59]
	v_mfma_f32_16x16x32_bf16 v[44:47], v[154:157], v[208:211], v[44:47]
	v_mfma_f32_16x16x32_bf16 v[40:43], v[176:179], v[208:211], v[40:43]
	v_mfma_f32_16x16x32_bf16 v[28:31], v[154:157], v[216:219], v[28:31]
	v_mfma_f32_16x16x32_bf16 v[24:27], v[176:179], v[216:219], v[24:27]
	v_mfma_f32_16x16x32_bf16 v[12:15], v[154:157], v[224:227], v[12:15]
	v_mfma_f32_16x16x32_bf16 v[8:11], v[176:179], v[224:227], v[8:11]
.Lp3q_skip_2:
	s_setprio 0
	s_setprio 1
	s_bitcmp1_b32 s100, 3
	s_cbranch_scc0 .Lp3q_skip_3
	v_mfma_f32_16x16x32_bf16 v[52:55], v[180:183], v[196:199], v[52:55]
	v_mfma_f32_16x16x32_bf16 v[48:51], v[188:191], v[196:199], v[48:51]
	v_mfma_f32_16x16x32_bf16 v[36:39], v[180:183], v[204:207], v[36:39]
	v_mfma_f32_16x16x32_bf16 v[32:35], v[188:191], v[204:207], v[32:35]
	v_mfma_f32_16x16x32_bf16 v[20:23], v[180:183], v[212:215], v[20:23]
	v_mfma_f32_16x16x32_bf16 v[16:19], v[188:191], v[212:215], v[16:19]
	v_mfma_f32_16x16x32_bf16 v[4:7], v[180:183], v[220:223], v[4:7]
	v_mfma_f32_16x16x32_bf16 v[0:3], v[188:191], v[220:223], v[0:3]
	v_mfma_f32_16x16x32_bf16 v[52:55], v[184:187], v[200:203], v[52:55]
	v_mfma_f32_16x16x32_bf16 v[48:51], v[192:195], v[200:203], v[48:51]
	v_mfma_f32_16x16x32_bf16 v[36:39], v[184:187], v[208:211], v[36:39]
	v_mfma_f32_16x16x32_bf16 v[32:35], v[192:195], v[208:211], v[32:35]
	v_mfma_f32_16x16x32_bf16 v[20:23], v[184:187], v[216:219], v[20:23]
	v_mfma_f32_16x16x32_bf16 v[16:19], v[192:195], v[216:219], v[16:19]
	v_mfma_f32_16x16x32_bf16 v[4:7], v[184:187], v[224:227], v[4:7]
	v_mfma_f32_16x16x32_bf16 v[0:3], v[192:195], v[224:227], v[0:3]
.Lp3q_skip_3:
	s_setprio 0
	s_barrier
	ds_read_b128 v[150:153], v163
	ds_read_b128 v[154:157], v163 offset:1024
	ds_read_b128 v[168:171], v163 offset:2048
	ds_read_b128 v[176:179], v163 offset:3072
	ds_read_b128 v[180:183], v164
	ds_read_b128 v[184:187], v164 offset:1024
	ds_read_b128 v[188:191], v164 offset:2048
	ds_read_b128 v[192:195], v164 offset:3072
	s_add_u32 s22, vcc_lo, 0x40000
	s_addc_u32 s23, vcc_hi, 0
	s_mov_b32 m0, s4
	v_lshl_add_u64 v[234:235], s[22:23], 0, v[140:141]
	ds_read_b128 v[196:199], v162 offset:32768
	ds_read_b128 v[200:203], v162 offset:33792
	ds_read_b128 v[204:207], v162 offset:34816
	ds_read_b128 v[208:211], v162 offset:35840
	ds_read_b128 v[212:215], v162 offset:36864
	ds_read_b128 v[216:219], v162 offset:37888
	ds_read_b128 v[220:223], v162 offset:38912
	ds_read_b128 v[224:227], v162 offset:39936
	global_load_lds_dwordx4 v[234:235], off
	v_lshl_add_u64 v[234:235], s[22:23], 0, v[144:145]
	s_mov_b32 m0, s5
	s_nop 0
	global_load_lds_dwordx4 v[234:235], off
	s_waitcnt vmcnt(8)
	s_waitcnt lgkmcnt(0)
	s_barrier
	s_setprio 1
	s_waitcnt lgkmcnt(0)
	s_bitcmp1_b32 s100, 0
	s_cbranch_scc0 .Lp3q_skip_4
	v_mfma_f32_16x16x32_bf16 v[124:127], v[150:153], v[196:199], v[124:127]
	v_mfma_f32_16x16x32_bf16 v[120:123], v[168:171], v[196:199], v[120:123]
	v_mfma_f32_16x16x32_bf16 v[108:111], v[150:153], v[204:207], v[108:111]
	v_mfma_f32_16x16x32_bf16 v[104:107], v[168:171], v[204:207], v[104:107]
	v_mfma_f32_16x16x32_bf16 v[92:95], v[150:153], v[212:215], v[92:95]
	v_mfma_f32_16x16x32_bf16 v[88:91], v[168:171], v[212:215], v[88:91]
	v_mfma_f32_16x16x32_bf16 v[76:79], v[150:153], v[220:223], v[76:79]
	v_mfma_f32_16x16x32_bf16 v[72:75], v[168:171], v[220:223], v[72:75]
	v_mfma_f32_16x16x32_bf16 v[124:127], v[154:157], v[200:203], v[124:127]
	v_mfma_f32_16x16x32_bf16 v[120:123], v[176:179], v[200:203], v[120:123]
	v_mfma_f32_16x16x32_bf16 v[108:111], v[154:157], v[208:211], v[108:111]
	v_mfma_f32_16x16x32_bf16 v[104:107], v[176:179], v[208:211], v[104:107]
	v_mfma_f32_16x16x32_bf16 v[92:95], v[154:157], v[216:219], v[92:95]
	v_mfma_f32_16x16x32_bf16 v[88:91], v[176:179], v[216:219], v[88:91]
	v_mfma_f32_16x16x32_bf16 v[76:79], v[154:157], v[224:227], v[76:79]
	v_mfma_f32_16x16x32_bf16 v[72:75], v[176:179], v[224:227], v[72:75]

; #define PG8_STAGE(bufoff, gbase, voff) do { _Pragma("unroll") for (int _i = 0; _i < 2; ++_i) \
;         __builtin_amdgcn_global_load_lds((const unsigned*)((const char*)(gbase) + (voff)[_i]), (PG8_LAS unsigned*)(lds + (bufoff) + ldsw + _i * 8192), 16, 0, 0); } while (0)
; #define PG8_LDA(dst, b, h) do { _Pragma("unroll") for (int m = 0; m < 4; ++m) _Pragma("unroll") for (int k = 0; k < 2; ++k) dst[m][k] = *(const PG8_LAS bf16x8*)(lds + PG8_SA(b, h) + aoff + m * 2048 + k * 1024); } while (0)
; #define PG8_LDB(dst, b, h) do { _Pragma("unroll") for (int n = 0; n < 2; ++n) _Pragma("unroll") for (int k = 0; k < 2; ++k) dst[n][k] = *(const PG8_LAS bf16x8*)(lds + PG8_SB(b, h) + boff + n * 2048 + k * 1024); } while (0)
; #define PG8_MMA(ai, bj, At, Bt) do { __builtin_amdgcn_s_setprio(1); _Pragma("unroll") for (int m = 0; m < 4; ++m) _Pragma("unroll") for (int n = 0; n < 2; ++n) _Pragma("unroll") for (int k = 0; k < 2; ++k) \
;         acc[ai][bj][m][n] = __builtin_amdgcn_mfma_f32_16x16x32_bf16(Bt[n][k], At[m][k], acc[ai][bj][m][n], 0, 0, 0); __builtin_amdgcn_s_setprio(0); } while (0)
; #define PG8_WAIT_V(n) asm volatile("s_waitcnt vmcnt(" #n ")" ::: "memory")
; #define PG8_WAIT_L(n) asm volatile("s_waitcnt lgkmcnt(" #n ")" ::: "memory")
; #define PG8_BAR __builtin_amdgcn_s_barrier()
; #define PG8_SCHED __builtin_amdgcn_sched_barrier(0)
; template <class Epi, class Sched, bool ALIGN_EPI = false, bool SP2 = false>
; __device__ __forceinline__ void gemm_phase(PG8_LAS unsigned char* lds, const Gemm g, const Sched& S, const Epi& E) {
;     ...
;             PG8_LDB(B0, 1, 0); PG8_LDB(B1, 1, 1); PG8_SCHED; PG8_LDA(At, 1, 0); PG8_STAGE(PG8_SA(0, 1), a2 + hstep, voffA);
;             PG8_WAIT_V(8); PG8_WAIT_L(0); PG8_BAR; PG8_MMA(0, 0, At, B0); PG8_MMA(0, 1, At, B1); PG8_BAR; PG8_SCHED;
;             PG8_LDA(At, 1, 1); PG8_STAGE(PG8_SB(1, 0), b3, voffB); PG8_STAGE(PG8_SB(1, 1), b3 + hstep, voffB); PG8_STAGE(PG8_SA(1, 0), a3, voffA);
;             PG8_WAIT_V(8); PG8_WAIT_L(0); PG8_BAR; PG8_MMA(1, 0, At, B0); PG8_MMA(1, 1, At, B1); PG8_BAR; PG8_SCHED;
.Lp3q_skip_5:
	s_setprio 0
	s_barrier
	s_add_i32 s22, s17, s3
	v_lshl_add_u64 v[172:173], v[172:173], 0, s[74:75]
	s_mov_b32 m0, s22
	ds_read_b128 v[196:199], v162 offset:49152
	ds_read_b128 v[200:203], v162 offset:50176
	ds_read_b128 v[204:207], v162 offset:51200
	ds_read_b128 v[208:211], v162 offset:52224
	ds_read_b128 v[212:215], v162 offset:53248
	ds_read_b128 v[216:219], v162 offset:54272
	ds_read_b128 v[220:223], v162 offset:55296
	ds_read_b128 v[224:227], v162 offset:56320
	global_load_lds_dwordx4 v[172:173], off
	s_add_i32 m0, s22, 0x2000
	s_add_u32 s22, s98, 0x40080
	v_lshl_add_u64 v[172:173], v[228:229], 0, s[74:75]
	s_addc_u32 s23, s99, 0
	s_add_i32 s24, s18, s3
	global_load_lds_dwordx4 v[172:173], off
	v_lshl_add_u64 v[172:173], s[22:23], 0, v[142:143]
	s_mov_b32 m0, s24
	s_nop 0
	global_load_lds_dwordx4 v[172:173], off
	v_lshl_add_u64 v[172:173], s[22:23], 0, v[146:147]
	s_add_i32 m0, s24, 0x2000
	s_nop 0
	global_load_lds_dwordx4 v[172:173], off
	v_lshl_add_u64 v[172:173], v[230:231], 0, s[74:75]
	s_mov_b32 m0, s6
	s_nop 0
	global_load_lds_dwordx4 v[172:173], off
	v_lshl_add_u64 v[172:173], v[232:233], 0, s[74:75]
	s_mov_b32 m0, s7
	s_nop 0
	global_load_lds_dwordx4 v[172:173], off
	s_waitcnt vmcnt(8)
	s_waitcnt lgkmcnt(0)
	s_barrier
	s_setprio 1
	s_waitcnt lgkmcnt(0)
	s_bitcmp1_b32 s100, 2
	s_cbranch_scc0 .Lp3q_skip_6
	v_mfma_f32_16x16x32_bf16 v[60:63], v[150:153], v[196:199], v[60:63]
	v_mfma_f32_16x16x32_bf16 v[56:59], v[168:171], v[196:199], v[56:59]
	v_mfma_f32_16x16x32_bf16 v[44:47], v[150:153], v[204:207], v[44:47]
	v_mfma_f32_16x16x32_bf16 v[40:43], v[168:171], v[204:207], v[40:43]
	v_mfma_f32_16x16x32_bf16 v[28:31], v[150:153], v[212:215], v[28:31]
	v_mfma_f32_16x16x32_bf16 v[24:27], v[168:171], v[212:215], v[24:27]
	v_mfma_f32_16x16x32_bf16 v[12:15], v[150:153], v[220:223], v[12:15]
	v_mfma_f32_16x16x32_bf16 v[8:11], v[168:171], v[220:223], v[8:11]
	v_mfma_f32_16x16x32_bf16 v[60:63], v[154:157], v[200:203], v[60:63]
	v_mfma_f32_16x16x32_bf16 v[56:59], v[176:179], v[200:203], v[56:59]
	v_mfma_f32_16x16x32_bf16 v[44:47], v[154:157], v[208:211], v[44:47]
	v_mfma_f32_16x16x32_bf16 v[40:43], v[176:179], v[208:211], v[40:43]
	v_mfma_f32_16x16x32_bf16 v[28:31], v[154:157], v[216:219], v[28:31]
	v_mfma_f32_16x16x32_bf16 v[24:27], v[176:179], v[216:219], v[24:27]
	v_mfma_f32_16x16x32_bf16 v[12:15], v[154:157], v[224:227], v[12:15]
	v_mfma_f32_16x16x32_bf16 v[8:11], v[176:179], v[224:227], v[8:11]

; #define PG8_WAIT_V(n) asm volatile("s_waitcnt vmcnt(" #n ")" ::: "memory")
; #define PG8_WAIT_L(n) asm volatile("s_waitcnt lgkmcnt(" #n ")" ::: "memory")
; template <class Epi, class Sched, bool ALIGN_EPI = false, bool SP2 = false>
; __device__ __forceinline__ void gemm_phase(PG8_LAS unsigned char* lds, const Gemm g, const Sched& S, const Epi& E) {
;     ...
;             PG8_WAIT_V(8); PG8_WAIT_L(0); PG8_BAR; PG8_MMA(1, 0, At, B0); PG8_MMA(1, 1, At, B1); PG8_BAR; PG8_SCHED;
;             } else {
;             PG8_LDB(B0, 0, 0); PG8_SCHED; PG8_LDA(At, 0, 0); PG8_STAGE(PG8_SA(1, 1), a1 + hstep, voffA);
;             PG8_WAIT_L(8); PG8_BAR; PG8_WAIT_L(0); PG8_MMA(0, 0, At, B0); PG8_BAR; PG8_SCHED;
;             PG8_LDB(B1, 0, 1); PG8_STAGE(PG8_SB(0, 0), b2, voffB);
;             PG8_BAR; PG8_WAIT_L(0); PG8_MMA(0, 1, At, B1); PG8_BAR;
;             PG8_LDA(At, 0, 1); PG8_STAGE(PG8_SA(0, 0), a2, voffA);
;             PG8_BAR; PG8_WAIT_L(0); PG8_MMA(1, 0, At, B0); PG8_BAR; PG8_SCHED;
;             PG8_STAGE(PG8_SB(0, 1), b2 + hstep, voffB);
;             PG8_WAIT_V(6); PG8_BAR; PG8_MMA(1, 1, At, B1); PG8_BAR;
;             PG8_LDB(B0, 1, 0); PG8_SCHED; PG8_LDA(At, 1, 0); PG8_STAGE(PG8_SA(0, 1), a2 + hstep, voffA);
;             PG8_WAIT_L(8); PG8_BAR; PG8_WAIT_L(0); PG8_MMA(0, 0, At, B0); PG8_BAR; PG8_SCHED;
;             PG8_LDB(B1, 1, 1); PG8_STAGE(PG8_SB(1, 0), b3, voffB);
;             PG8_BAR; PG8_WAIT_L(0); PG8_MMA(0, 1, At, B1); PG8_BAR;
;             PG8_LDA(At, 1, 1); PG8_STAGE(PG8_SA(1, 0), a3, voffA);
;             PG8_BAR; PG8_WAIT_L(0); PG8_MMA(1, 0, At, B0); PG8_BAR; PG8_SCHED;
;             PG8_STAGE(PG8_SB(1, 1), b3 + hstep, voffB);
;             PG8_WAIT_V(6); PG8_BAR; PG8_MMA(1, 1, At, B1); PG8_BAR;
;             }
;         }
;         if constexpr (ALIGN_EPI) { if (wr == 0) PG8_BAR; }
;         if constexpr (!Epi::AFTER_DRAIN) { E(acc, cur, wr, wc, fr, fq); S.done(cur); }
;     DI void operator()(const f32x4 (&acc)[2][2][4][2], const pg8::Unit& u, int wr, int wc, int fr, int fq) const {
;         const Params& p = *pp;
;         const int colt = u.pn * 256;
; #pragma unroll
;         for (int ai = 0; ai < 2; ++ai)
; #pragma unroll
;             for (int m = 0; m < 4; ++m) {
;                 const int R = u.pm * 256 + ai * 128 + wr * 64 + m * 16 + fr;
;                 const float* xs = nullptr; float* yd = nullptr;
.Lp3q_skip_7:
	s_setprio 0
	s_barrier
	s_add_i32 s21, s21, 2
	s_add_u32 s96, s96, 0x100
	s_addc_u32 s97, s97, 0
	s_add_u32 s95, s95, 0x100
	s_addc_u32 s20, s20, 0
	s_cmp_gt_u32 s21, 13
	s_cbranch_scc0 .LBB0_617
	s_and_b64 vcc, exec, s[80:81]
	s_cbranch_vccz .LBB0_620
	s_barrier
.LBB0_620:
	s_cmp_eq_u32 s100, 15
	s_cbranch_scc0 .Lp3q_epi
	v_lshl_add_u32 v150, s94, 8, v158
	v_cmp_lt_i32_e32 vcc, s13, v150
	s_and_saveexec_b64 s[20:21], vcc
	s_xor_b64 s[94:95], exec, s[20:21]
	v_add_u32_e32 v132, 0xffffbf00, v150
	v_lshlrev_b64 v[152:153], 12, v[132:133]
	v_lshl_add_u64 v[156:157], s[78:79], 0, v[152:153]
	v_lshl_add_u64 v[154:155], s[82:83], 0, v[152:153]
	s_andn2_saveexec_b64 s[94:95], s[94:95]
	s_cbranch_execz .LBB0_626
	v_mul_hi_i32 v132, v150, s14
	v_lshrrev_b32_e32 v151, 31, v132
	v_ashrrev_i32_e32 v132, 11, v132
	v_add_u32_e32 v152, v132, v151
	v_mad_i32_i24 v132, v152, s15, v150
	v_add_u32_e32 v151, -16, v132
	v_cmp_gt_u32_e32 vcc, s16, v151
	v_mov_b64_e32 v[156:157], 0
	v_mov_b64_e32 v[154:155], 0
	s_and_saveexec_b64 s[96:97], vcc
	v_ashrrev_i32_e32 v153, 31, v152
	v_lshlrev_b64 v[152:153], 22, v[152:153]
	v_lshlrev_b32_e32 v132, 10, v132
	v_lshl_add_u64 v[152:153], v[152:153], 0, v[132:133]
	v_lshl_add_u64 v[152:153], v[152:153], 2, s[84:85]
	v_lshl_add_u64 v[156:157], s[76:77], 0, v[152:153]
	v_lshl_add_u64 v[154:155], s[54:55], 0, v[152:153]
	s_or_b64 exec, exec, s[96:97]

;     DI void operator()(const f32x4 (&acc)[2][2][4][2], const pg8::Unit& u, int wr, int wc, int fr, int fq) const {
;         const Params& p = *pp;
;         const int colt = u.pn * 256;
; #pragma unroll
;         for (int ai = 0; ai < 2; ++ai)
; #pragma unroll
;             for (int m = 0; m < 4; ++m) {
;                 const int R = u.pm * 256 + ai * 128 + wr * 64 + m * 16 + fr;
;                 const float* xs = nullptr; float* yd = nullptr;
;                 if (R < ROWS_P) { const int b = R / LPAD, t = R - b * LPAD; if (t >= NMETA && t < LP) { const size_t idx = ((size_t)b * SEQ + t - NMETA) * DM; xs = p.x_prompt + idx; yd = p.out + O_YP + idx; } }
;                 else { const size_t idx = (size_t)(R - ROWS_P) * DM; xs = p.x_sample + idx; yd = p.out + O_YS + idx; }
;                 float ss = 0.f;
;                 if (xs) {
; #pragma unroll
;                     for (int bj = 0; bj < 2; ++bj) {
;                         const int n = colt + bj * 128 + wc * 32 + 8 * fq;
;                         const f32x4 x0 = *(const f32x4*)(xs + n), x1 = *(const f32x4*)(xs + n + 4);
;                         const f32x4 h0 = x0 + acc[ai][bj][m][0], h1 = x1 + acc[ai][bj][m][1];
;                         *(f32x4*)(yd + n) = h0; *(f32x4*)(yd + n + 4) = h1;
;                         ss += h0[0] * h0[0] + h0[1] * h0[1] + h0[2] * h0[2] + h0[3] * h0[3] + h1[0] * h1[0] + h1[1] * h1[1] + h1[2] * h1[2] + h1[3] * h1[3];
;                     }
;                 }
;                 ss += __shfl_xor(ss, 16); ss += __shfl_xor(ss, 32);
;                 if (xs && fq == 0) atomicAdd(p.rowss + R, ss);
;             }
;     }
.Lp3q_epi_done:
	s_andn2_b64 vcc, exec, s[38:39]
	s_mov_b64 s[38:39], -1
	s_cbranch_vccnz .LBB0_609
	s_andn2_b64 vcc, exec, s[72:73]
	s_cbranch_vccnz .LBB0_608
	s_barrier
	s_branch .LBB0_608
.Lp3q_epi:
	v_lshl_add_u32 v150, s94, 8, v158
	v_lshl_or_b32 v152, s42, 8, v159
	v_and_b32_e32 v151, 15, v158
	v_lshlrev_b32_e32 v152, 2, v152
	v_lshl_or_b32 v151, v151, 12, v152
	v_lshlrev_b32_e32 v152, 2, v150
	v_xor_b32_e32 v153, 16, v174
	v_xor_b32_e32 v154, 32, v174
	v_lshlrev_b32_e32 v153, 2, v153
	v_lshlrev_b32_e32 v154, 2, v154
	s_and_b64 s[20:21], s[72:73], exec
	s_cselect_b32 s20, 64, 0
	s_lshl_b32 s21, s94, 8
	s_add_i32 s21, s21, s20
	s_cmp_ge_u32 s94, 65
	s_cselect_b32 s96, s78, s76
	s_cselect_b32 s97, s79, s77
	s_cselect_b32 s98, s82, s54
	s_cselect_b32 s99, s83, s55
	s_mov_b32 s19, 0
	s_bitcmp1_b32 s100, 0
	s_cbranch_scc1 .Lp3q_v0
	s_bitcmp1_b32 s100, 1
	s_cbranch_scc1 .Lp3q_v1
	s_bitcmp1_b32 s100, 2
	s_cbranch_scc1 .Lp3q_v2
	s_branch .Lp3q_v3
.Lp3q_v0:
	s_add_i32 s87, s21, 0
	s_mul_hi_u32 s89, s87, 0x7e07e07f
	s_lshr_b32 s89, s89, 11
	s_mul_i32 vcc_lo, s89, 0x1040
	s_sub_i32 vcc_lo, s87, vcc_lo
	s_add_i32 vcc_lo, vcc_lo, -16
	s_lshl_b32 s89, s89, 12
	s_add_i32 s89, s89, vcc_lo
	s_cmp_lt_u32 vcc_lo, 0x1000
	s_cselect_b32 vcc_hi, 1, 0
	s_sub_i32 vcc_lo, s87, 0x4100
	s_cmp_ge_u32 s94, 65
	s_cselect_b32 s89, vcc_lo, s89
	s_cselect_b32 vcc_hi, 1, vcc_hi
	s_cmp_lg_u32 vcc_hi, 0
	s_cselect_b32 s89, s89, 0
	s_lshl_b32 s20, s89, 12
	s_lshl_b32 vcc_hi, vcc_hi, 0
	s_or_b32 s19, s19, vcc_hi
	s_add_u32 s22, s96, s20
	s_addc_u32 s23, s97, 0
	global_load_dwordx4 v[176:179], v151, s[22:23]
	global_load_dwordx4 v[180:183], v151, s[22:23] offset:16
	s_add_i32 s87, s21, 16
	s_mul_hi_u32 s89, s87, 0x7e07e07f
	s_lshr_b32 s89, s89, 11
	s_mul_i32 vcc_lo, s89, 0x1040
	s_sub_i32 vcc_lo, s87, vcc_lo
	s_add_i32 vcc_lo, vcc_lo, -16
	s_lshl_b32 s89, s89, 12
	s_add_i32 s89, s89, vcc_lo
	s_cmp_lt_u32 vcc_lo, 0x1000
	s_cselect_b32 vcc_hi, 1, 0
	s_sub_i32 vcc_lo, s87, 0x4100
	s_cmp_ge_u32 s94, 65
	s_cselect_b32 s89, vcc_lo, s89
	s_cselect_b32 vcc_hi, 1, vcc_hi
	s_cmp_lg_u32 vcc_hi, 0
	s_cselect_b32 s89, s89, 0
	s_lshl_b32 s42, s89, 12
	s_lshl_b32 vcc_hi, vcc_hi, 1
	s_or_b32 s19, s19, vcc_hi
	s_add_u32 s22, s96, s42
	s_addc_u32 s23, s97, 0
	global_load_dwordx4 v[184:187], v151, s[22:23]
	global_load_dwordx4 v[188:191], v151, s[22:23] offset:16
	s_add_i32 s87, s21, 32
	s_mul_hi_u32 s89, s87, 0x7e07e07f
	s_lshr_b32 s89, s89, 11
	s_mul_i32 vcc_lo, s89, 0x1040
	s_sub_i32 vcc_lo, s87, vcc_lo
	s_add_i32 vcc_lo, vcc_lo, -16
	s_lshl_b32 s89, s89, 12
	s_add_i32 s89, s89, vcc_lo
	s_cmp_lt_u32 vcc_lo, 0x1000
	s_cselect_b32 vcc_hi, 1, 0
	s_sub_i32 vcc_lo, s87, 0x4100
	s_cmp_ge_u32 s94, 65
	s_cselect_b32 s89, vcc_lo, s89
	s_cselect_b32 vcc_hi, 1, vcc_hi
	s_cmp_lg_u32 vcc_hi, 0
	s_cselect_b32 s89, s89, 0
	s_lshl_b32 s43, s89, 12
	s_lshl_b32 vcc_hi, vcc_hi, 2
	s_or_b32 s19, s19, vcc_hi
	s_add_u32 s22, s96, s43
	s_addc_u32 s23, s97, 0
	global_load_dwordx4 v[192:195], v151, s[22:23]
	global_load_dwordx4 v[196:199], v151, s[22:23] offset:16
	s_add_i32 s87, s21, 48
	s_mul_hi_u32 s89, s87, 0x7e07e07f
	s_lshr_b32 s89, s89, 11
	s_mul_i32 vcc_lo, s89, 0x1040
	s_sub_i32 vcc_lo, s87, vcc_lo
	s_add_i32 vcc_lo, vcc_lo, -16
	s_lshl_b32 s89, s89, 12
	s_add_i32 s89, s89, vcc_lo
	s_cmp_lt_u32 vcc_lo, 0x1000
	s_cselect_b32 vcc_hi, 1, 0
	s_sub_i32 vcc_lo, s87, 0x4100
	s_cmp_ge_u32 s94, 65
	s_cselect_b32 s89, vcc_lo, s89
	s_cselect_b32 vcc_hi, 1, vcc_hi
	s_cmp_lg_u32 vcc_hi, 0
	s_cselect_b32 s89, s89, 0
	s_lshl_b32 s95, s89, 12
	s_lshl_b32 vcc_hi, vcc_hi, 3
	s_or_b32 s19, s19, vcc_hi
	s_add_u32 s22, s96, s95
	s_addc_u32 s23, s97, 0
	global_load_dwordx4 v[200:203], v151, s[22:23]
	global_load_dwordx4 v[204:207], v151, s[22:23] offset:16
	s_waitcnt vmcnt(0)
	v_pk_add_f32 v[124:125], v[124:125], v[176:177]
	v_pk_add_f32 v[126:127], v[126:127], v[178:179]
	v_pk_add_f32 v[120:121], v[120:121], v[180:181]
	v_pk_add_f32 v[122:123], v[122:123], v[182:183]
	v_pk_mul_f32 v[172:173], v[124:125], v[124:125]
	v_pk_fma_f32 v[172:173], v[126:127], v[126:127], v[172:173]
	v_pk_fma_f32 v[172:173], v[120:121], v[120:121], v[172:173]
	v_pk_fma_f32 v[172:173], v[122:123], v[122:123], v[172:173]
	s_bitcmp1_b32 s19, 0
	s_cbranch_scc0 .Lp3q_ss_0_0
	s_add_u32 s22, s98, s20
	s_addc_u32 s23, s99, 0
	global_store_dwordx4 v151, v[124:127], s[22:23]
	global_store_dwordx4 v151, v[120:123], s[22:23] offset:16
;     DI void operator()(const f32x4 (&acc)[2][2][4][2], const pg8::Unit& u, int wr, int wc, int fr, int fq) const {
;     ...
;                 float ss = 0.f;
;                 if (xs) {
; #pragma unroll
;                     for (int bj = 0; bj < 2; ++bj) {
;                         const int n = colt + bj * 128 + wc * 32 + 8 * fq;
;                         const f32x4 x0 = *(const f32x4*)(xs + n), x1 = *(const f32x4*)(xs + n + 4);
;                         const f32x4 h0 = x0 + acc[ai][bj][m][0], h1 = x1 + acc[ai][bj][m][1];
;                         *(f32x4*)(yd + n) = h0; *(f32x4*)(yd + n + 4) = h1;
;                         ss += h0[0] * h0[0] + h0[1] * h0[1] + h0[2] * h0[2] + h0[3] * h0[3] + h1[0] * h1[0] + h1[1] * h1[1] + h1[2] * h1[2] + h1[3] * h1[3];
;                     }
;                 }
;                 ss += __shfl_xor(ss, 16); ss += __shfl_xor(ss, 32);
;                 if (xs && fq == 0) atomicAdd(p.rowss + R, ss);
;             }
.Lp3q_ss_0_0:
	v_add_f32_e32 v168, v172, v173
	v_pk_add_f32 v[108:109], v[108:109], v[184:185]
	v_pk_add_f32 v[110:111], v[110:111], v[186:187]
	v_pk_add_f32 v[104:105], v[104:105], v[188:189]
	v_pk_add_f32 v[106:107], v[106:107], v[190:191]
	v_pk_mul_f32 v[172:173], v[108:109], v[108:109]
	v_pk_fma_f32 v[172:173], v[110:111], v[110:111], v[172:173]
	v_pk_fma_f32 v[172:173], v[104:105], v[104:105], v[172:173]
	v_pk_fma_f32 v[172:173], v[106:107], v[106:107], v[172:173]
	s_bitcmp1_b32 s19, 1
	s_cbranch_scc0 .Lp3q_ss_0_1
	s_add_u32 s22, s98, s42
	s_addc_u32 s23, s99, 0
	global_store_dwordx4 v151, v[108:111], s[22:23]
	global_store_dwordx4 v151, v[104:107], s[22:23] offset:16
.Lp3q_ss_0_1:
	v_add_f32_e32 v169, v172, v173
	v_pk_add_f32 v[92:93], v[92:93], v[192:193]
	v_pk_add_f32 v[94:95], v[94:95], v[194:195]
	v_pk_add_f32 v[88:89], v[88:89], v[196:197]
	v_pk_add_f32 v[90:91], v[90:91], v[198:199]
	v_pk_mul_f32 v[172:173], v[92:93], v[92:93]
	v_pk_fma_f32 v[172:173], v[94:95], v[94:95], v[172:173]
	v_pk_fma_f32 v[172:173], v[88:89], v[88:89], v[172:173]
	v_pk_fma_f32 v[172:173], v[90:91], v[90:91], v[172:173]
	s_bitcmp1_b32 s19, 2
	s_cbranch_scc0 .Lp3q_ss_0_2
	s_add_u32 s22, s98, s43
	s_addc_u32 s23, s99, 0
	global_store_dwordx4 v151, v[92:95], s[22:23]
	global_store_dwordx4 v151, v[88:91], s[22:23] offset:16
.Lp3q_ss_0_2:
	v_add_f32_e32 v170, v172, v173
	v_pk_add_f32 v[76:77], v[76:77], v[200:201]
	v_pk_add_f32 v[78:79], v[78:79], v[202:203]
	v_pk_add_f32 v[72:73], v[72:73], v[204:205]
	v_pk_add_f32 v[74:75], v[74:75], v[206:207]
	v_pk_mul_f32 v[172:173], v[76:77], v[76:77]
	v_pk_fma_f32 v[172:173], v[78:79], v[78:79], v[172:173]
	v_pk_fma_f32 v[172:173], v[72:73], v[72:73], v[172:173]
	v_pk_fma_f32 v[172:173], v[74:75], v[74:75], v[172:173]
	s_bitcmp1_b32 s19, 3
	s_cbranch_scc0 .Lp3q_ss_0_3
	s_add_u32 s22, s98, s95
	s_addc_u32 s23, s99, 0
	global_store_dwordx4 v151, v[76:79], s[22:23]
	global_store_dwordx4 v151, v[72:75], s[22:23] offset:16
.Lp3q_ss_0_3:
	v_add_f32_e32 v171, v172, v173
	ds_bpermute_b32 v155, v153, v168
	ds_bpermute_b32 v156, v153, v169
	ds_bpermute_b32 v157, v153, v170
	ds_bpermute_b32 v132, v153, v171
	s_waitcnt lgkmcnt(0)
	v_add_f32_e32 v168, v168, v155
	v_add_f32_e32 v169, v169, v156
	v_add_f32_e32 v170, v170, v157
	v_add_f32_e32 v171, v171, v132
	ds_bpermute_b32 v155, v154, v168
	ds_bpermute_b32 v156, v154, v169
	ds_bpermute_b32 v157, v154, v170
	ds_bpermute_b32 v132, v154, v171
	s_waitcnt lgkmcnt(0)
	v_add_f32_e32 v168, v168, v155
	v_add_f32_e32 v169, v169, v156
	v_add_f32_e32 v170, v170, v157
	v_add_f32_e32 v171, v171, v132
	s_mov_b64 exec, s[36:37]
	s_bitcmp1_b32 s19, 0
	s_cbranch_scc0 .Lp3q_at_0_0
	global_atomic_add_f32 v152, v168, s[60:61]

;     DI void operator()(const f32x4 (&acc)[2][2][4][2], const pg8::Unit& u, int wr, int wc, int fr, int fq) const {
;         const Params& p = *pp;
;         const int colt = u.pn * 256;
; #pragma unroll
;         for (int ai = 0; ai < 2; ++ai)
; #pragma unroll
;             for (int m = 0; m < 4; ++m) {
;                 const int R = u.pm * 256 + ai * 128 + wr * 64 + m * 16 + fr;
;                 const float* xs = nullptr; float* yd = nullptr;
;                 if (R < ROWS_P) { const int b = R / LPAD, t = R - b * LPAD; if (t >= NMETA && t < LP) { const size_t idx = ((size_t)b * SEQ + t - NMETA) * DM; xs = p.x_prompt + idx; yd = p.out + O_YP + idx; } }
;                 else { const size_t idx = (size_t)(R - ROWS_P) * DM; xs = p.x_sample + idx; yd = p.out + O_YS + idx; }
;                 float ss = 0.f;
;                 if (xs) {
; #pragma unroll
;                     for (int bj = 0; bj < 2; ++bj) {
;                         const int n = colt + bj * 128 + wc * 32 + 8 * fq;
;                         const f32x4 x0 = *(const f32x4*)(xs + n), x1 = *(const f32x4*)(xs + n + 4);
;                         const f32x4 h0 = x0 + acc[ai][bj][m][0], h1 = x1 + acc[ai][bj][m][1];
;                         *(f32x4*)(yd + n) = h0; *(f32x4*)(yd + n + 4) = h1;
;                         ss += h0[0] * h0[0] + h0[1] * h0[1] + h0[2] * h0[2] + h0[3] * h0[3] + h1[0] * h1[0] + h1[1] * h1[1] + h1[2] * h1[2] + h1[3] * h1[3];
;                     }
;                 }
;                 ss += __shfl_xor(ss, 16); ss += __shfl_xor(ss, 32);
;                 if (xs && fq == 0) atomicAdd(p.rowss + R, ss);
;             }
.Lp3q_at_0_3:
	s_mov_b64 exec, -1
	s_branch .Lp3q_epi_done
.Lp3q_v1:
	s_add_i32 s87, s21, 0
	s_mul_hi_u32 s89, s87, 0x7e07e07f
	s_lshr_b32 s89, s89, 11
	s_mul_i32 vcc_lo, s89, 0x1040
	s_sub_i32 vcc_lo, s87, vcc_lo
	s_add_i32 vcc_lo, vcc_lo, -16
	s_lshl_b32 s89, s89, 12
	s_add_i32 s89, s89, vcc_lo
	s_cmp_lt_u32 vcc_lo, 0x1000
	s_cselect_b32 vcc_hi, 1, 0
	s_sub_i32 vcc_lo, s87, 0x4100
	s_cmp_ge_u32 s94, 65
	s_cselect_b32 s89, vcc_lo, s89
	s_cselect_b32 vcc_hi, 1, vcc_hi
	s_cmp_lg_u32 vcc_hi, 0
	s_cselect_b32 s89, s89, 0
	s_lshl_b32 s20, s89, 12
	s_lshl_b32 vcc_hi, vcc_hi, 0
	s_or_b32 s19, s19, vcc_hi
	s_add_u32 s22, s96, s20
	s_addc_u32 s23, s97, 0
	global_load_dwordx4 v[176:179], v151, s[22:23] offset:512
	global_load_dwordx4 v[180:183], v151, s[22:23] offset:528
	s_add_i32 s87, s21, 16
	s_mul_hi_u32 s89, s87, 0x7e07e07f
	s_lshr_b32 s89, s89, 11
	s_mul_i32 vcc_lo, s89, 0x1040
	s_sub_i32 vcc_lo, s87, vcc_lo
	s_add_i32 vcc_lo, vcc_lo, -16
	s_lshl_b32 s89, s89, 12
	s_add_i32 s89, s89, vcc_lo
	s_cmp_lt_u32 vcc_lo, 0x1000
	s_cselect_b32 vcc_hi, 1, 0
	s_sub_i32 vcc_lo, s87, 0x4100
	s_cmp_ge_u32 s94, 65
	s_cselect_b32 s89, vcc_lo, s89
	s_cselect_b32 vcc_hi, 1, vcc_hi
	s_cmp_lg_u32 vcc_hi, 0
	s_cselect_b32 s89, s89, 0
	s_lshl_b32 s42, s89, 12
	s_lshl_b32 vcc_hi, vcc_hi, 1
	s_or_b32 s19, s19, vcc_hi
	s_add_u32 s22, s96, s42
	s_addc_u32 s23, s97, 0
	global_load_dwordx4 v[184:187], v151, s[22:23] offset:512
	global_load_dwordx4 v[188:191], v151, s[22:23] offset:528
	s_add_i32 s87, s21, 32
	s_mul_hi_u32 s89, s87, 0x7e07e07f
	s_lshr_b32 s89, s89, 11
	s_mul_i32 vcc_lo, s89, 0x1040
	s_sub_i32 vcc_lo, s87, vcc_lo
	s_add_i32 vcc_lo, vcc_lo, -16
	s_lshl_b32 s89, s89, 12
	s_add_i32 s89, s89, vcc_lo
	s_cmp_lt_u32 vcc_lo, 0x1000
	s_cselect_b32 vcc_hi, 1, 0
	s_sub_i32 vcc_lo, s87, 0x4100
	s_cmp_ge_u32 s94, 65
	s_cselect_b32 s89, vcc_lo, s89
	s_cselect_b32 vcc_hi, 1, vcc_hi
	s_cmp_lg_u32 vcc_hi, 0
	s_cselect_b32 s89, s89, 0
	s_lshl_b32 s43, s89, 12
	s_lshl_b32 vcc_hi, vcc_hi, 2
	s_or_b32 s19, s19, vcc_hi
	s_add_u32 s22, s96, s43
	s_addc_u32 s23, s97, 0
	global_load_dwordx4 v[192:195], v151, s[22:23] offset:512
	global_load_dwordx4 v[196:199], v151, s[22:23] offset:528
	s_add_i32 s87, s21, 48
	s_mul_hi_u32 s89, s87, 0x7e07e07f
	s_lshr_b32 s89, s89, 11
	s_mul_i32 vcc_lo, s89, 0x1040
	s_sub_i32 vcc_lo, s87, vcc_lo
	s_add_i32 vcc_lo, vcc_lo, -16
	s_lshl_b32 s89, s89, 12
	s_add_i32 s89, s89, vcc_lo
	s_cmp_lt_u32 vcc_lo, 0x1000
	s_cselect_b32 vcc_hi, 1, 0
	s_sub_i32 vcc_lo, s87, 0x4100
	s_cmp_ge_u32 s94, 65
	s_cselect_b32 s89, vcc_lo, s89
	s_cselect_b32 vcc_hi, 1, vcc_hi
	s_cmp_lg_u32 vcc_hi, 0
	s_cselect_b32 s89, s89, 0
	s_lshl_b32 s95, s89, 12
	s_lshl_b32 vcc_hi, vcc_hi, 3
	s_or_b32 s19, s19, vcc_hi
	s_add_u32 s22, s96, s95
	s_addc_u32 s23, s97, 0
	global_load_dwordx4 v[200:203], v151, s[22:23] offset:512
	global_load_dwordx4 v[204:207], v151, s[22:23] offset:528
	s_waitcnt vmcnt(0)
	v_pk_add_f32 v[116:117], v[116:117], v[176:177]
	v_pk_add_f32 v[118:119], v[118:119], v[178:179]
	v_pk_add_f32 v[112:113], v[112:113], v[180:181]
	v_pk_add_f32 v[114:115], v[114:115], v[182:183]
	v_pk_mul_f32 v[172:173], v[116:117], v[116:117]
	v_pk_fma_f32 v[172:173], v[118:119], v[118:119], v[172:173]
	v_pk_fma_f32 v[172:173], v[112:113], v[112:113], v[172:173]
	v_pk_fma_f32 v[172:173], v[114:115], v[114:115], v[172:173]
	s_bitcmp1_b32 s19, 0
	s_cbranch_scc0 .Lp3q_ss_1_0
	s_add_u32 s22, s98, s20
	s_addc_u32 s23, s99, 0
	global_store_dwordx4 v151, v[116:119], s[22:23] offset:512
	global_store_dwordx4 v151, v[112:115], s[22:23] offset:528
.Lp3q_ss_1_0:
	v_add_f32_e32 v168, v172, v173
	v_pk_add_f32 v[100:101], v[100:101], v[184:185]
	v_pk_add_f32 v[102:103], v[102:103], v[186:187]
	v_pk_add_f32 v[96:97], v[96:97], v[188:189]
	v_pk_add_f32 v[98:99], v[98:99], v[190:191]
	v_pk_mul_f32 v[172:173], v[100:101], v[100:101]
	v_pk_fma_f32 v[172:173], v[102:103], v[102:103], v[172:173]
	v_pk_fma_f32 v[172:173], v[96:97], v[96:97], v[172:173]
	v_pk_fma_f32 v[172:173], v[98:99], v[98:99], v[172:173]
	s_bitcmp1_b32 s19, 1
	s_cbranch_scc0 .Lp3q_ss_1_1
	s_add_u32 s22, s98, s42
	s_addc_u32 s23, s99, 0
	global_store_dwordx4 v151, v[100:103], s[22:23] offset:512
	global_store_dwordx4 v151, v[96:99], s[22:23] offset:528
.Lp3q_ss_1_1:
	v_add_f32_e32 v169, v172, v173
	v_pk_add_f32 v[84:85], v[84:85], v[192:193]
	v_pk_add_f32 v[86:87], v[86:87], v[194:195]
	v_pk_add_f32 v[80:81], v[80:81], v[196:197]
	v_pk_add_f32 v[82:83], v[82:83], v[198:199]
	v_pk_mul_f32 v[172:173], v[84:85], v[84:85]
	v_pk_fma_f32 v[172:173], v[86:87], v[86:87], v[172:173]
	v_pk_fma_f32 v[172:173], v[80:81], v[80:81], v[172:173]
	v_pk_fma_f32 v[172:173], v[82:83], v[82:83], v[172:173]
	s_bitcmp1_b32 s19, 2
	s_cbranch_scc0 .Lp3q_ss_1_2
	s_add_u32 s22, s98, s43
	s_addc_u32 s23, s99, 0
	global_store_dwordx4 v151, v[84:87], s[22:23] offset:512
	global_store_dwordx4 v151, v[80:83], s[22:23] offset:528
.Lp3q_ss_1_2:
	v_add_f32_e32 v170, v172, v173
	v_pk_add_f32 v[68:69], v[68:69], v[200:201]
	v_pk_add_f32 v[70:71], v[70:71], v[202:203]
	v_pk_add_f32 v[64:65], v[64:65], v[204:205]
	v_pk_add_f32 v[66:67], v[66:67], v[206:207]
	v_pk_mul_f32 v[172:173], v[68:69], v[68:69]
	v_pk_fma_f32 v[172:173], v[70:71], v[70:71], v[172:173]
	v_pk_fma_f32 v[172:173], v[64:65], v[64:65], v[172:173]
	v_pk_fma_f32 v[172:173], v[66:67], v[66:67], v[172:173]
	s_bitcmp1_b32 s19, 3
	s_cbranch_scc0 .Lp3q_ss_1_3
	s_add_u32 s22, s98, s95
	s_addc_u32 s23, s99, 0
	global_store_dwordx4 v151, v[68:71], s[22:23] offset:512
	global_store_dwordx4 v151, v[64:67], s[22:23] offset:528

;     DI void operator()(const f32x4 (&acc)[2][2][4][2], const pg8::Unit& u, int wr, int wc, int fr, int fq) const {
;         const Params& p = *pp;
;         const int colt = u.pn * 256;
; #pragma unroll
;         for (int ai = 0; ai < 2; ++ai)
; #pragma unroll
;             for (int m = 0; m < 4; ++m) {
;                 const int R = u.pm * 256 + ai * 128 + wr * 64 + m * 16 + fr;
;                 const float* xs = nullptr; float* yd = nullptr;
;                 if (R < ROWS_P) { const int b = R / LPAD, t = R - b * LPAD; if (t >= NMETA && t < LP) { const size_t idx = ((size_t)b * SEQ + t - NMETA) * DM; xs = p.x_prompt + idx; yd = p.out + O_YP + idx; } }
;                 else { const size_t idx = (size_t)(R - ROWS_P) * DM; xs = p.x_sample + idx; yd = p.out + O_YS + idx; }
;                 float ss = 0.f;
;                 if (xs) {
; #pragma unroll
;                     for (int bj = 0; bj < 2; ++bj) {
;                         const int n = colt + bj * 128 + wc * 32 + 8 * fq;
;                         const f32x4 x0 = *(const f32x4*)(xs + n), x1 = *(const f32x4*)(xs + n + 4);
;                         const f32x4 h0 = x0 + acc[ai][bj][m][0], h1 = x1 + acc[ai][bj][m][1];
;                         *(f32x4*)(yd + n) = h0; *(f32x4*)(yd + n + 4) = h1;
;                         ss += h0[0] * h0[0] + h0[1] * h0[1] + h0[2] * h0[2] + h0[3] * h0[3] + h1[0] * h1[0] + h1[1] * h1[1] + h1[2] * h1[2] + h1[3] * h1[3];
;                     }
;                 }
;                 ss += __shfl_xor(ss, 16); ss += __shfl_xor(ss, 32);
;                 if (xs && fq == 0) atomicAdd(p.rowss + R, ss);
;             }
.Lp3q_v2:
	s_add_i32 s87, s21, 128
	s_mul_hi_u32 s89, s87, 0x7e07e07f
	s_lshr_b32 s89, s89, 11
	s_mul_i32 vcc_lo, s89, 0x1040
	s_sub_i32 vcc_lo, s87, vcc_lo
	s_add_i32 vcc_lo, vcc_lo, -16
	s_lshl_b32 s89, s89, 12
	s_add_i32 s89, s89, vcc_lo
	s_cmp_lt_u32 vcc_lo, 0x1000
	s_cselect_b32 vcc_hi, 1, 0
	s_sub_i32 vcc_lo, s87, 0x4100
	s_cmp_ge_u32 s94, 65
	s_cselect_b32 s89, vcc_lo, s89
	s_cselect_b32 vcc_hi, 1, vcc_hi
	s_cmp_lg_u32 vcc_hi, 0
	s_cselect_b32 s89, s89, 0
	s_lshl_b32 s20, s89, 12
	s_lshl_b32 vcc_hi, vcc_hi, 0
	s_or_b32 s19, s19, vcc_hi
	s_add_u32 s22, s96, s20
	s_addc_u32 s23, s97, 0
	global_load_dwordx4 v[176:179], v151, s[22:23]
	global_load_dwordx4 v[180:183], v151, s[22:23] offset:16
	s_add_i32 s87, s21, 144
	s_mul_hi_u32 s89, s87, 0x7e07e07f
	s_lshr_b32 s89, s89, 11
	s_mul_i32 vcc_lo, s89, 0x1040
	s_sub_i32 vcc_lo, s87, vcc_lo
	s_add_i32 vcc_lo, vcc_lo, -16
	s_lshl_b32 s89, s89, 12
	s_add_i32 s89, s89, vcc_lo
	s_cmp_lt_u32 vcc_lo, 0x1000
	s_cselect_b32 vcc_hi, 1, 0
	s_sub_i32 vcc_lo, s87, 0x4100
	s_cmp_ge_u32 s94, 65
	s_cselect_b32 s89, vcc_lo, s89
	s_cselect_b32 vcc_hi, 1, vcc_hi
	s_cmp_lg_u32 vcc_hi, 0
	s_cselect_b32 s89, s89, 0
	s_lshl_b32 s42, s89, 12
	s_lshl_b32 vcc_hi, vcc_hi, 1
	s_or_b32 s19, s19, vcc_hi
	s_add_u32 s22, s96, s42
	s_addc_u32 s23, s97, 0
	global_load_dwordx4 v[184:187], v151, s[22:23]
	global_load_dwordx4 v[188:191], v151, s[22:23] offset:16
	s_add_i32 s87, s21, 160
	s_mul_hi_u32 s89, s87, 0x7e07e07f
	s_lshr_b32 s89, s89, 11
	s_mul_i32 vcc_lo, s89, 0x1040
	s_sub_i32 vcc_lo, s87, vcc_lo
	s_add_i32 vcc_lo, vcc_lo, -16
	s_lshl_b32 s89, s89, 12
	s_add_i32 s89, s89, vcc_lo
	s_cmp_lt_u32 vcc_lo, 0x1000
	s_cselect_b32 vcc_hi, 1, 0
	s_sub_i32 vcc_lo, s87, 0x4100
	s_cmp_ge_u32 s94, 65
	s_cselect_b32 s89, vcc_lo, s89
	s_cselect_b32 vcc_hi, 1, vcc_hi
	s_cmp_lg_u32 vcc_hi, 0
	s_cselect_b32 s89, s89, 0
	s_lshl_b32 s43, s89, 12
	s_lshl_b32 vcc_hi, vcc_hi, 2
	s_or_b32 s19, s19, vcc_hi
	s_add_u32 s22, s96, s43
	s_addc_u32 s23, s97, 0
	global_load_dwordx4 v[192:195], v151, s[22:23]
	global_load_dwordx4 v[196:199], v151, s[22:23] offset:16
	s_add_i32 s87, s21, 176
	s_mul_hi_u32 s89, s87, 0x7e07e07f
	s_lshr_b32 s89, s89, 11
	s_mul_i32 vcc_lo, s89, 0x1040
	s_sub_i32 vcc_lo, s87, vcc_lo
	s_add_i32 vcc_lo, vcc_lo, -16
	s_lshl_b32 s89, s89, 12
	s_add_i32 s89, s89, vcc_lo
	s_cmp_lt_u32 vcc_lo, 0x1000
	s_cselect_b32 vcc_hi, 1, 0
	s_sub_i32 vcc_lo, s87, 0x4100
	s_cmp_ge_u32 s94, 65
	s_cselect_b32 s89, vcc_lo, s89
	s_cselect_b32 vcc_hi, 1, vcc_hi
	s_cmp_lg_u32 vcc_hi, 0
	s_cselect_b32 s89, s89, 0
	s_lshl_b32 s95, s89, 12
	s_lshl_b32 vcc_hi, vcc_hi, 3
	s_or_b32 s19, s19, vcc_hi
	s_add_u32 s22, s96, s95
	s_addc_u32 s23, s97, 0
	global_load_dwordx4 v[200:203], v151, s[22:23]
	global_load_dwordx4 v[204:207], v151, s[22:23] offset:16
	s_waitcnt vmcnt(0)
	v_pk_add_f32 v[60:61], v[60:61], v[176:177]
	v_pk_add_f32 v[62:63], v[62:63], v[178:179]
	v_pk_add_f32 v[56:57], v[56:57], v[180:181]
	v_pk_add_f32 v[58:59], v[58:59], v[182:183]
	v_pk_mul_f32 v[172:173], v[60:61], v[60:61]
	v_pk_fma_f32 v[172:173], v[62:63], v[62:63], v[172:173]
	v_pk_fma_f32 v[172:173], v[56:57], v[56:57], v[172:173]
	v_pk_fma_f32 v[172:173], v[58:59], v[58:59], v[172:173]
	s_bitcmp1_b32 s19, 0
	s_cbranch_scc0 .Lp3q_ss_2_0
	s_add_u32 s22, s98, s20
	s_addc_u32 s23, s99, 0
	global_store_dwordx4 v151, v[60:63], s[22:23]
	global_store_dwordx4 v151, v[56:59], s[22:23] offset:16
.Lp3q_ss_2_0:
	v_add_f32_e32 v168, v172, v173
	v_pk_add_f32 v[44:45], v[44:45], v[184:185]
	v_pk_add_f32 v[46:47], v[46:47], v[186:187]
	v_pk_add_f32 v[40:41], v[40:41], v[188:189]
	v_pk_add_f32 v[42:43], v[42:43], v[190:191]
	v_pk_mul_f32 v[172:173], v[44:45], v[44:45]
	v_pk_fma_f32 v[172:173], v[46:47], v[46:47], v[172:173]
	v_pk_fma_f32 v[172:173], v[40:41], v[40:41], v[172:173]
	v_pk_fma_f32 v[172:173], v[42:43], v[42:43], v[172:173]
	s_bitcmp1_b32 s19, 1
	s_cbranch_scc0 .Lp3q_ss_2_1
	s_add_u32 s22, s98, s42
	s_addc_u32 s23, s99, 0
	global_store_dwordx4 v151, v[44:47], s[22:23]
	global_store_dwordx4 v151, v[40:43], s[22:23] offset:16
.Lp3q_ss_2_1:
	v_add_f32_e32 v169, v172, v173
	v_pk_add_f32 v[28:29], v[28:29], v[192:193]
	v_pk_add_f32 v[30:31], v[30:31], v[194:195]
	v_pk_add_f32 v[24:25], v[24:25], v[196:197]
	v_pk_add_f32 v[26:27], v[26:27], v[198:199]
	v_pk_mul_f32 v[172:173], v[28:29], v[28:29]
	v_pk_fma_f32 v[172:173], v[30:31], v[30:31], v[172:173]
	v_pk_fma_f32 v[172:173], v[24:25], v[24:25], v[172:173]
	v_pk_fma_f32 v[172:173], v[26:27], v[26:27], v[172:173]
	s_bitcmp1_b32 s19, 2
	s_cbranch_scc0 .Lp3q_ss_2_2
	s_add_u32 s22, s98, s43
	s_addc_u32 s23, s99, 0
	global_store_dwordx4 v151, v[28:31], s[22:23]
	global_store_dwordx4 v151, v[24:27], s[22:23] offset:16
.Lp3q_ss_2_2:
	v_add_f32_e32 v170, v172, v173
	v_pk_add_f32 v[12:13], v[12:13], v[200:201]
	v_pk_add_f32 v[14:15], v[14:15], v[202:203]
	v_pk_add_f32 v[8:9], v[8:9], v[204:205]
	v_pk_add_f32 v[10:11], v[10:11], v[206:207]
	v_pk_mul_f32 v[172:173], v[12:13], v[12:13]
	v_pk_fma_f32 v[172:173], v[14:15], v[14:15], v[172:173]
	v_pk_fma_f32 v[172:173], v[8:9], v[8:9], v[172:173]
	v_pk_fma_f32 v[172:173], v[10:11], v[10:11], v[172:173]
	s_bitcmp1_b32 s19, 3
	s_cbranch_scc0 .Lp3q_ss_2_3
	s_add_u32 s22, s98, s95
	s_addc_u32 s23, s99, 0
	global_store_dwordx4 v151, v[12:15], s[22:23]
	global_store_dwordx4 v151, v[8:11], s[22:23] offset:16
.Lp3q_ss_2_3:
	v_add_f32_e32 v171, v172, v173
	ds_bpermute_b32 v155, v153, v168
	ds_bpermute_b32 v156, v153, v169
	ds_bpermute_b32 v157, v153, v170
	ds_bpermute_b32 v132, v153, v171
	s_waitcnt lgkmcnt(0)
	v_add_f32_e32 v168, v168, v155
	v_add_f32_e32 v169, v169, v156
	v_add_f32_e32 v170, v170, v157
	v_add_f32_e32 v171, v171, v132
	ds_bpermute_b32 v155, v154, v168
	ds_bpermute_b32 v156, v154, v169
	ds_bpermute_b32 v157, v154, v170
	ds_bpermute_b32 v132, v154, v171
	s_waitcnt lgkmcnt(0)
	v_add_f32_e32 v168, v168, v155
	v_add_f32_e32 v169, v169, v156
	v_add_f32_e32 v170, v170, v157
	v_add_f32_e32 v171, v171, v132
	s_mov_b64 exec, s[36:37]
	s_bitcmp1_b32 s19, 0
	s_cbranch_scc0 .Lp3q_at_2_0
	global_atomic_add_f32 v152, v168, s[60:61] offset:512
.Lp3q_at_2_0:
	s_bitcmp1_b32 s19, 1
	s_cbranch_scc0 .Lp3q_at_2_1
	global_atomic_add_f32 v152, v169, s[60:61] offset:576
.Lp3q_at_2_1:
	s_bitcmp1_b32 s19, 2
	s_cbranch_scc0 .Lp3q_at_2_2
	global_atomic_add_f32 v152, v170, s[60:61] offset:640
.Lp3q_at_2_2:
	s_bitcmp1_b32 s19, 3
	s_cbranch_scc0 .Lp3q_at_2_3
	global_atomic_add_f32 v152, v171, s[60:61] offset:704

;     DI void operator()(const f32x4 (&acc)[2][2][4][2], const pg8::Unit& u, int wr, int wc, int fr, int fq) const {
;         const Params& p = *pp;
;         const int colt = u.pn * 256;
; #pragma unroll
;         for (int ai = 0; ai < 2; ++ai)
; #pragma unroll
;             for (int m = 0; m < 4; ++m) {
;                 const int R = u.pm * 256 + ai * 128 + wr * 64 + m * 16 + fr;
;                 const float* xs = nullptr; float* yd = nullptr;
;                 if (R < ROWS_P) { const int b = R / LPAD, t = R - b * LPAD; if (t >= NMETA && t < LP) { const size_t idx = ((size_t)b * SEQ + t - NMETA) * DM; xs = p.x_prompt + idx; yd = p.out + O_YP + idx; } }
;                 else { const size_t idx = (size_t)(R - ROWS_P) * DM; xs = p.x_sample + idx; yd = p.out + O_YS + idx; }
;                 float ss = 0.f;
;                 if (xs) {
; #pragma unroll
;                     for (int bj = 0; bj < 2; ++bj) {
;                         const int n = colt + bj * 128 + wc * 32 + 8 * fq;
;                         const f32x4 x0 = *(const f32x4*)(xs + n), x1 = *(const f32x4*)(xs + n + 4);
;                         const f32x4 h0 = x0 + acc[ai][bj][m][0], h1 = x1 + acc[ai][bj][m][1];
;                         *(f32x4*)(yd + n) = h0; *(f32x4*)(yd + n + 4) = h1;
;                         ss += h0[0] * h0[0] + h0[1] * h0[1] + h0[2] * h0[2] + h0[3] * h0[3] + h1[0] * h1[0] + h1[1] * h1[1] + h1[2] * h1[2] + h1[3] * h1[3];
;                     }
;                 }
;                 ss += __shfl_xor(ss, 16); ss += __shfl_xor(ss, 32);
;                 if (xs && fq == 0) atomicAdd(p.rowss + R, ss);
;             }
.Lp3q_v3:
	s_add_i32 s87, s21, 128
	s_mul_hi_u32 s89, s87, 0x7e07e07f
	s_lshr_b32 s89, s89, 11
	s_mul_i32 vcc_lo, s89, 0x1040
	s_sub_i32 vcc_lo, s87, vcc_lo
	s_add_i32 vcc_lo, vcc_lo, -16
	s_lshl_b32 s89, s89, 12
	s_add_i32 s89, s89, vcc_lo
	s_cmp_lt_u32 vcc_lo, 0x1000
	s_cselect_b32 vcc_hi, 1, 0
	s_sub_i32 vcc_lo, s87, 0x4100
	s_cmp_ge_u32 s94, 65
	s_cselect_b32 s89, vcc_lo, s89
	s_cselect_b32 vcc_hi, 1, vcc_hi
	s_cmp_lg_u32 vcc_hi, 0
	s_cselect_b32 s89, s89, 0
	s_lshl_b32 s20, s89, 12
	s_lshl_b32 vcc_hi, vcc_hi, 0
	s_or_b32 s19, s19, vcc_hi
	s_add_u32 s22, s96, s20
	s_addc_u32 s23, s97, 0
	global_load_dwordx4 v[176:179], v151, s[22:23] offset:512
	global_load_dwordx4 v[180:183], v151, s[22:23] offset:528
	s_add_i32 s87, s21, 144
	s_mul_hi_u32 s89, s87, 0x7e07e07f
	s_lshr_b32 s89, s89, 11
	s_mul_i32 vcc_lo, s89, 0x1040
	s_sub_i32 vcc_lo, s87, vcc_lo
	s_add_i32 vcc_lo, vcc_lo, -16
	s_lshl_b32 s89, s89, 12
	s_add_i32 s89, s89, vcc_lo
	s_cmp_lt_u32 vcc_lo, 0x1000
	s_cselect_b32 vcc_hi, 1, 0
	s_sub_i32 vcc_lo, s87, 0x4100
	s_cmp_ge_u32 s94, 65
	s_cselect_b32 s89, vcc_lo, s89
	s_cselect_b32 vcc_hi, 1, vcc_hi
	s_cmp_lg_u32 vcc_hi, 0
	s_cselect_b32 s89, s89, 0
	s_lshl_b32 s42, s89, 12
	s_lshl_b32 vcc_hi, vcc_hi, 1
	s_or_b32 s19, s19, vcc_hi
	s_add_u32 s22, s96, s42
	s_addc_u32 s23, s97, 0
	global_load_dwordx4 v[184:187], v151, s[22:23] offset:512
	global_load_dwordx4 v[188:191], v151, s[22:23] offset:528
	s_add_i32 s87, s21, 160
	s_mul_hi_u32 s89, s87, 0x7e07e07f
	s_lshr_b32 s89, s89, 11
	s_mul_i32 vcc_lo, s89, 0x1040
	s_sub_i32 vcc_lo, s87, vcc_lo
	s_add_i32 vcc_lo, vcc_lo, -16
	s_lshl_b32 s89, s89, 12
	s_add_i32 s89, s89, vcc_lo
	s_cmp_lt_u32 vcc_lo, 0x1000
	s_cselect_b32 vcc_hi, 1, 0
	s_sub_i32 vcc_lo, s87, 0x4100
	s_cmp_ge_u32 s94, 65
	s_cselect_b32 s89, vcc_lo, s89
	s_cselect_b32 vcc_hi, 1, vcc_hi
	s_cmp_lg_u32 vcc_hi, 0
	s_cselect_b32 s89, s89, 0
	s_lshl_b32 s43, s89, 12
	s_lshl_b32 vcc_hi, vcc_hi, 2
	s_or_b32 s19, s19, vcc_hi
	s_add_u32 s22, s96, s43
	s_addc_u32 s23, s97, 0
	global_load_dwordx4 v[192:195], v151, s[22:23] offset:512
	global_load_dwordx4 v[196:199], v151, s[22:23] offset:528
	s_add_i32 s87, s21, 176
	s_mul_hi_u32 s89, s87, 0x7e07e07f
	s_lshr_b32 s89, s89, 11
	s_mul_i32 vcc_lo, s89, 0x1040
	s_sub_i32 vcc_lo, s87, vcc_lo
	s_add_i32 vcc_lo, vcc_lo, -16
	s_lshl_b32 s89, s89, 12
	s_add_i32 s89, s89, vcc_lo
	s_cmp_lt_u32 vcc_lo, 0x1000
	s_cselect_b32 vcc_hi, 1, 0
	s_sub_i32 vcc_lo, s87, 0x4100
	s_cmp_ge_u32 s94, 65
	s_cselect_b32 s89, vcc_lo, s89
	s_cselect_b32 vcc_hi, 1, vcc_hi
	s_cmp_lg_u32 vcc_hi, 0
	s_cselect_b32 s89, s89, 0
	s_lshl_b32 s95, s89, 12
	s_lshl_b32 vcc_hi, vcc_hi, 3
	s_or_b32 s19, s19, vcc_hi
	s_add_u32 s22, s96, s95
	s_addc_u32 s23, s97, 0
	global_load_dwordx4 v[200:203], v151, s[22:23] offset:512
	global_load_dwordx4 v[204:207], v151, s[22:23] offset:528
	s_waitcnt vmcnt(0)
	v_pk_add_f32 v[52:53], v[52:53], v[176:177]
	v_pk_add_f32 v[54:55], v[54:55], v[178:179]
	v_pk_add_f32 v[48:49], v[48:49], v[180:181]
	v_pk_add_f32 v[50:51], v[50:51], v[182:183]
	v_pk_mul_f32 v[172:173], v[52:53], v[52:53]
	v_pk_fma_f32 v[172:173], v[54:55], v[54:55], v[172:173]
	v_pk_fma_f32 v[172:173], v[48:49], v[48:49], v[172:173]
	v_pk_fma_f32 v[172:173], v[50:51], v[50:51], v[172:173]
	s_bitcmp1_b32 s19, 0
	s_cbranch_scc0 .Lp3q_ss_3_0
	s_add_u32 s22, s98, s20
	s_addc_u32 s23, s99, 0
	global_store_dwordx4 v151, v[52:55], s[22:23] offset:512
	global_store_dwordx4 v151, v[48:51], s[22:23] offset:528
.Lp3q_ss_3_0:
	v_add_f32_e32 v168, v172, v173
	v_pk_add_f32 v[36:37], v[36:37], v[184:185]
	v_pk_add_f32 v[38:39], v[38:39], v[186:187]
	v_pk_add_f32 v[32:33], v[32:33], v[188:189]
	v_pk_add_f32 v[34:35], v[34:35], v[190:191]
	v_pk_mul_f32 v[172:173], v[36:37], v[36:37]
	v_pk_fma_f32 v[172:173], v[38:39], v[38:39], v[172:173]
	v_pk_fma_f32 v[172:173], v[32:33], v[32:33], v[172:173]
	v_pk_fma_f32 v[172:173], v[34:35], v[34:35], v[172:173]
	s_bitcmp1_b32 s19, 1
	s_cbranch_scc0 .Lp3q_ss_3_1
	s_add_u32 s22, s98, s42
	s_addc_u32 s23, s99, 0
	global_store_dwordx4 v151, v[36:39], s[22:23] offset:512
	global_store_dwordx4 v151, v[32:35], s[22:23] offset:528
.Lp3q_ss_3_1:
	v_add_f32_e32 v169, v172, v173
	v_pk_add_f32 v[20:21], v[20:21], v[192:193]
	v_pk_add_f32 v[22:23], v[22:23], v[194:195]
	v_pk_add_f32 v[16:17], v[16:17], v[196:197]
	v_pk_add_f32 v[18:19], v[18:19], v[198:199]
	v_pk_mul_f32 v[172:173], v[20:21], v[20:21]
	v_pk_fma_f32 v[172:173], v[22:23], v[22:23], v[172:173]
	v_pk_fma_f32 v[172:173], v[16:17], v[16:17], v[172:173]
	v_pk_fma_f32 v[172:173], v[18:19], v[18:19], v[172:173]
	s_bitcmp1_b32 s19, 2
	s_cbranch_scc0 .Lp3q_ss_3_2
	s_add_u32 s22, s98, s43
	s_addc_u32 s23, s99, 0
	global_store_dwordx4 v151, v[20:23], s[22:23] offset:512
	global_store_dwordx4 v151, v[16:19], s[22:23] offset:528
.Lp3q_ss_3_2:
	v_add_f32_e32 v170, v172, v173
	v_pk_add_f32 v[4:5], v[4:5], v[200:201]
	v_pk_add_f32 v[6:7], v[6:7], v[202:203]
	v_pk_add_f32 v[0:1], v[0:1], v[204:205]
	v_pk_add_f32 v[2:3], v[2:3], v[206:207]
	v_pk_mul_f32 v[172:173], v[4:5], v[4:5]
	v_pk_fma_f32 v[172:173], v[6:7], v[6:7], v[172:173]
	v_pk_fma_f32 v[172:173], v[0:1], v[0:1], v[172:173]
	v_pk_fma_f32 v[172:173], v[2:3], v[2:3], v[172:173]
	s_bitcmp1_b32 s19, 3
	s_cbranch_scc0 .Lp3q_ss_3_3
	s_add_u32 s22, s98, s95
	s_addc_u32 s23, s99, 0
	global_store_dwordx4 v151, v[4:7], s[22:23] offset:512
	global_store_dwordx4 v151, v[0:3], s[22:23] offset:528
